# nt hint on the weight (B operand) LDS-DMA loads of the gate/up K-loops, on top of sc1 stores
# baseline (speedup 1.0000x reference)
.LBB0_137:
	ds_read_b128 v[146:149], v178
	ds_read_b128 v[150:153], v178 offset:1024
	ds_read_b128 v[154:157], v178 offset:2048
	ds_read_b128 v[158:161], v178 offset:3072
	ds_read_b128 v[182:185], v179
	ds_read_b128 v[186:189], v179 offset:1024
	ds_read_b128 v[190:193], v179 offset:2048
	ds_read_b128 v[194:197], v179 offset:3072
	s_add_u32 s30, s28, 0xfffc0080
	s_addc_u32 s31, s29, -1
	s_cmp_eq_u32 s72, 12
	s_cselect_b32 s35, s21, s31
	s_cselect_b32 s34, s68, s30
	s_cselect_b32 s31, s19, s71
	s_cselect_b32 s30, s69, s70
	v_lshl_add_u64 v[162:163], s[28:29], 0, v[138:139]
	s_add_i32 m0, s27, 0xc000
	ds_read_b128 v[198:201], v180
	ds_read_b128 v[202:205], v180 offset:1024
	ds_read_b128 v[206:209], v180 offset:2048
	ds_read_b128 v[210:213], v180 offset:3072
	ds_read_b128 v[214:217], v180 offset:4096
	ds_read_b128 v[218:221], v180 offset:5120
	ds_read_b128 v[222:225], v180 offset:6144
	ds_read_b128 v[226:229], v180 offset:7168
	global_load_lds_dwordx4 v[162:163], off
	v_lshl_add_u64 v[162:163], s[28:29], 0, v[140:141]
	s_add_i32 m0, s27, 0xe000
	s_nop 0
	global_load_lds_dwordx4 v[162:163], off
	s_waitcnt vmcnt(8)
	s_waitcnt lgkmcnt(0)
	s_barrier
	s_setprio 1
	s_waitcnt lgkmcnt(0)
	v_mfma_i32_16x16x64_i8 v[126:129], v[146:149], v[198:201], v[126:129]
	v_mfma_i32_16x16x64_i8 v[118:121], v[154:157], v[198:201], v[118:121]
	v_mfma_i32_16x16x64_i8 v[110:113], v[146:149], v[206:209], v[110:113]
	v_mfma_i32_16x16x64_i8 v[102:105], v[154:157], v[206:209], v[102:105]
	v_mfma_i32_16x16x64_i8 v[94:97], v[146:149], v[214:217], v[94:97]
	v_mfma_i32_16x16x64_i8 v[86:89], v[154:157], v[214:217], v[86:89]
	v_mfma_i32_16x16x64_i8 v[78:81], v[146:149], v[222:225], v[78:81]
	v_mfma_i32_16x16x64_i8 v[70:73], v[154:157], v[222:225], v[70:73]
	v_mfma_i32_16x16x64_i8 v[126:129], v[150:153], v[202:205], v[126:129]
	v_mfma_i32_16x16x64_i8 v[118:121], v[158:161], v[202:205], v[118:121]
	v_mfma_i32_16x16x64_i8 v[110:113], v[150:153], v[210:213], v[110:113]
	v_mfma_i32_16x16x64_i8 v[102:105], v[158:161], v[210:213], v[102:105]
	v_mfma_i32_16x16x64_i8 v[94:97], v[150:153], v[218:221], v[94:97]
	v_mfma_i32_16x16x64_i8 v[86:89], v[158:161], v[218:221], v[86:89]
	v_mfma_i32_16x16x64_i8 v[78:81], v[150:153], v[226:229], v[78:81]
	v_mfma_i32_16x16x64_i8 v[70:73], v[158:161], v[226:229], v[70:73]
	s_setprio 0
	s_setprio 1
	v_mfma_i32_16x16x64_i8 v[122:125], v[182:185], v[198:201], v[122:125]
	v_mfma_i32_16x16x64_i8 v[114:117], v[190:193], v[198:201], v[114:117]
	v_mfma_i32_16x16x64_i8 v[106:109], v[182:185], v[206:209], v[106:109]
	v_mfma_i32_16x16x64_i8 v[98:101], v[190:193], v[206:209], v[98:101]
	v_mfma_i32_16x16x64_i8 v[90:93], v[182:185], v[214:217], v[90:93]
	v_mfma_i32_16x16x64_i8 v[82:85], v[190:193], v[214:217], v[82:85]
	v_mfma_i32_16x16x64_i8 v[74:77], v[182:185], v[222:225], v[74:77]
	v_mfma_i32_16x16x64_i8 v[66:69], v[190:193], v[222:225], v[66:69]
	v_mfma_i32_16x16x64_i8 v[122:125], v[186:189], v[202:205], v[122:125]
	v_mfma_i32_16x16x64_i8 v[114:117], v[194:197], v[202:205], v[114:117]
	v_mfma_i32_16x16x64_i8 v[106:109], v[186:189], v[210:213], v[106:109]
	v_mfma_i32_16x16x64_i8 v[98:101], v[194:197], v[210:213], v[98:101]
	v_mfma_i32_16x16x64_i8 v[90:93], v[186:189], v[218:221], v[90:93]
	v_mfma_i32_16x16x64_i8 v[82:85], v[194:197], v[218:221], v[82:85]
	v_mfma_i32_16x16x64_i8 v[74:77], v[186:189], v[226:229], v[74:77]
	v_mfma_i32_16x16x64_i8 v[66:69], v[194:197], v[226:229], v[66:69]
	s_setprio 0
	s_barrier
	s_add_i32 s73, s46, s38
	v_lshl_add_u64 v[162:163], s[30:31], 0, v[134:135]
	s_mov_b32 m0, s73
	ds_read_b128 v[198:201], v180 offset:16384
	ds_read_b128 v[202:205], v180 offset:17408
	ds_read_b128 v[206:209], v180 offset:18432
	ds_read_b128 v[210:213], v180 offset:19456
	ds_read_b128 v[214:217], v180 offset:20480
	ds_read_b128 v[218:221], v180 offset:21504
	ds_read_b128 v[222:225], v180 offset:22528
	ds_read_b128 v[226:229], v180 offset:23552
	global_load_lds_dwordx4 v[162:163], off nt
	s_add_i32 m0, s73, 0x2000
	s_add_u32 s74, s30, 0x40000
	v_lshl_add_u64 v[230:231], s[30:31], 0, v[130:131]
	s_addc_u32 s75, s31, 0
	s_add_i32 s73, s47, s38
	global_load_lds_dwordx4 v[230:231], off nt
	v_lshl_add_u64 v[232:233], s[74:75], 0, v[134:135]
	s_mov_b32 m0, s73
	v_lshl_add_u64 v[234:235], s[34:35], 0, v[132:133]
	global_load_lds_dwordx4 v[232:233], off nt
	v_lshl_add_u64 v[232:233], s[74:75], 0, v[130:131]
	s_add_i32 m0, s73, 0x2000
	s_nop 0
	global_load_lds_dwordx4 v[232:233], off nt
	v_lshl_add_u64 v[232:233], s[34:35], 0, v[136:137]
	s_mov_b32 m0, s27
	s_nop 0
	global_load_lds_dwordx4 v[232:233], off
	s_mov_b32 m0, s40
	s_nop 0
	global_load_lds_dwordx4 v[234:235], off
	s_waitcnt vmcnt(8)
	s_waitcnt lgkmcnt(0)
	s_barrier
	s_setprio 1
	s_waitcnt lgkmcnt(0)
	v_mfma_i32_16x16x64_i8 v[62:65], v[146:149], v[198:201], v[62:65]
	v_mfma_i32_16x16x64_i8 v[54:57], v[154:157], v[198:201], v[54:57]
	v_mfma_i32_16x16x64_i8 v[46:49], v[146:149], v[206:209], v[46:49]
	v_mfma_i32_16x16x64_i8 v[38:41], v[154:157], v[206:209], v[38:41]
	v_mfma_i32_16x16x64_i8 v[30:33], v[146:149], v[214:217], v[30:33]
	v_mfma_i32_16x16x64_i8 v[22:25], v[154:157], v[214:217], v[22:25]
	v_mfma_i32_16x16x64_i8 v[14:17], v[146:149], v[222:225], v[14:17]
	v_mfma_i32_16x16x64_i8 v[6:9], v[154:157], v[222:225], v[6:9]
	v_mfma_i32_16x16x64_i8 v[62:65], v[150:153], v[202:205], v[62:65]
	v_mfma_i32_16x16x64_i8 v[54:57], v[158:161], v[202:205], v[54:57]
	v_mfma_i32_16x16x64_i8 v[46:49], v[150:153], v[210:213], v[46:49]
	v_mfma_i32_16x16x64_i8 v[38:41], v[158:161], v[210:213], v[38:41]
	v_mfma_i32_16x16x64_i8 v[30:33], v[150:153], v[218:221], v[30:33]
	v_mfma_i32_16x16x64_i8 v[22:25], v[158:161], v[218:221], v[22:25]
	v_mfma_i32_16x16x64_i8 v[14:17], v[150:153], v[226:229], v[14:17]
	v_mfma_i32_16x16x64_i8 v[6:9], v[158:161], v[226:229], v[6:9]
	s_setprio 0
	s_setprio 1
	v_mfma_i32_16x16x64_i8 v[58:61], v[182:185], v[198:201], v[58:61]
	v_mfma_i32_16x16x64_i8 v[50:53], v[190:193], v[198:201], v[50:53]
	v_mfma_i32_16x16x64_i8 v[42:45], v[182:185], v[206:209], v[42:45]
	v_mfma_i32_16x16x64_i8 v[34:37], v[190:193], v[206:209], v[34:37]
	v_mfma_i32_16x16x64_i8 v[26:29], v[182:185], v[214:217], v[26:29]
	v_mfma_i32_16x16x64_i8 v[18:21], v[190:193], v[214:217], v[18:21]
	v_mfma_i32_16x16x64_i8 v[10:13], v[182:185], v[222:225], v[10:13]
	v_mfma_i32_16x16x64_i8 v[2:5], v[190:193], v[222:225], v[2:5]
	v_mfma_i32_16x16x64_i8 v[58:61], v[186:189], v[202:205], v[58:61]
	v_mfma_i32_16x16x64_i8 v[50:53], v[194:197], v[202:205], v[50:53]
	v_mfma_i32_16x16x64_i8 v[42:45], v[186:189], v[210:213], v[42:45]
	v_mfma_i32_16x16x64_i8 v[34:37], v[194:197], v[210:213], v[34:37]
	v_mfma_i32_16x16x64_i8 v[26:29], v[186:189], v[218:221], v[26:29]
	v_mfma_i32_16x16x64_i8 v[18:21], v[194:197], v[218:221], v[18:21]
	v_mfma_i32_16x16x64_i8 v[10:13], v[186:189], v[226:229], v[10:13]
	v_mfma_i32_16x16x64_i8 v[2:5], v[194:197], v[226:229], v[2:5]
	s_setprio 0
	s_barrier
	s_add_i32 s73, 0, 0x18000
	v_add_u32_e32 v158, s73, v169
	ds_read_b128 v[146:149], v158
	ds_read_b128 v[150:153], v158 offset:1024
	ds_read_b128 v[154:157], v158 offset:2048
	ds_read_b128 v[158:161], v158 offset:3072
	ds_read_b128 v[182:185], v181
	ds_read_b128 v[186:189], v181 offset:1024
	ds_read_b128 v[190:193], v181 offset:2048
	ds_read_b128 v[194:197], v181 offset:3072
	s_add_u32 s34, s34, 0x40000
	s_addc_u32 s35, s35, 0
	s_mov_b32 m0, s41
	v_lshl_add_u64 v[236:237], s[34:35], 0, v[136:137]
	ds_read_b128 v[198:201], v180 offset:32768
	ds_read_b128 v[202:205], v180 offset:33792
	ds_read_b128 v[206:209], v180 offset:34816
	ds_read_b128 v[210:213], v180 offset:35840
	ds_read_b128 v[214:217], v180 offset:36864
	ds_read_b128 v[218:221], v180 offset:37888
	ds_read_b128 v[222:225], v180 offset:38912
	ds_read_b128 v[226:229], v180 offset:39936
	global_load_lds_dwordx4 v[236:237], off
	v_lshl_add_u64 v[236:237], s[34:35], 0, v[132:133]
	s_mov_b32 m0, s42
	s_nop 0
	global_load_lds_dwordx4 v[236:237], off
	s_waitcnt vmcnt(8)
	s_waitcnt lgkmcnt(0)
	s_barrier
	s_setprio 1
	s_waitcnt lgkmcnt(0)
	v_mfma_i32_16x16x64_i8 v[126:129], v[146:149], v[198:201], v[126:129]
	v_mfma_i32_16x16x64_i8 v[118:121], v[154:157], v[198:201], v[118:121]
	v_mfma_i32_16x16x64_i8 v[110:113], v[146:149], v[206:209], v[110:113]
	v_mfma_i32_16x16x64_i8 v[102:105], v[154:157], v[206:209], v[102:105]
	v_mfma_i32_16x16x64_i8 v[94:97], v[146:149], v[214:217], v[94:97]
	v_mfma_i32_16x16x64_i8 v[86:89], v[154:157], v[214:217], v[86:89]
	v_mfma_i32_16x16x64_i8 v[78:81], v[146:149], v[222:225], v[78:81]
	v_mfma_i32_16x16x64_i8 v[70:73], v[154:157], v[222:225], v[70:73]
	v_mfma_i32_16x16x64_i8 v[126:129], v[150:153], v[202:205], v[126:129]
	v_mfma_i32_16x16x64_i8 v[118:121], v[158:161], v[202:205], v[118:121]
	v_mfma_i32_16x16x64_i8 v[110:113], v[150:153], v[210:213], v[110:113]
	v_mfma_i32_16x16x64_i8 v[102:105], v[158:161], v[210:213], v[102:105]
	v_mfma_i32_16x16x64_i8 v[94:97], v[150:153], v[218:221], v[94:97]
	v_mfma_i32_16x16x64_i8 v[86:89], v[158:161], v[218:221], v[86:89]
	v_mfma_i32_16x16x64_i8 v[78:81], v[150:153], v[226:229], v[78:81]
	v_mfma_i32_16x16x64_i8 v[70:73], v[158:161], v[226:229], v[70:73]
	s_setprio 0
	s_setprio 1
	v_mfma_i32_16x16x64_i8 v[122:125], v[182:185], v[198:201], v[122:125]
	v_mfma_i32_16x16x64_i8 v[114:117], v[190:193], v[198:201], v[114:117]
	v_mfma_i32_16x16x64_i8 v[106:109], v[182:185], v[206:209], v[106:109]
	v_mfma_i32_16x16x64_i8 v[98:101], v[190:193], v[206:209], v[98:101]
	v_mfma_i32_16x16x64_i8 v[90:93], v[182:185], v[214:217], v[90:93]
	v_mfma_i32_16x16x64_i8 v[82:85], v[190:193], v[214:217], v[82:85]
	v_mfma_i32_16x16x64_i8 v[74:77], v[182:185], v[222:225], v[74:77]
	v_mfma_i32_16x16x64_i8 v[66:69], v[190:193], v[222:225], v[66:69]
	v_mfma_i32_16x16x64_i8 v[122:125], v[186:189], v[202:205], v[122:125]
	v_mfma_i32_16x16x64_i8 v[114:117], v[194:197], v[202:205], v[114:117]
	v_mfma_i32_16x16x64_i8 v[106:109], v[186:189], v[210:213], v[106:109]
	v_mfma_i32_16x16x64_i8 v[98:101], v[194:197], v[210:213], v[98:101]
	v_mfma_i32_16x16x64_i8 v[90:93], v[186:189], v[218:221], v[90:93]
	v_mfma_i32_16x16x64_i8 v[82:85], v[194:197], v[218:221], v[82:85]
	v_mfma_i32_16x16x64_i8 v[74:77], v[186:189], v[226:229], v[74:77]
	v_mfma_i32_16x16x64_i8 v[66:69], v[194:197], v[226:229], v[66:69]
	s_setprio 0
	s_barrier
	s_add_i32 s34, s73, s38
	v_lshl_add_u64 v[162:163], v[162:163], 0, s[10:11]
	s_mov_b32 m0, s34
	ds_read_b128 v[198:201], v180 offset:49152
	ds_read_b128 v[202:205], v180 offset:50176
	ds_read_b128 v[206:209], v180 offset:51200
	ds_read_b128 v[210:213], v180 offset:52224
	ds_read_b128 v[214:217], v180 offset:53248
	ds_read_b128 v[218:221], v180 offset:54272
	ds_read_b128 v[222:225], v180 offset:55296
	ds_read_b128 v[226:229], v180 offset:56320
	global_load_lds_dwordx4 v[162:163], off nt
	s_add_i32 m0, s34, 0x2000
	s_add_u32 s30, s30, 0x40080
	v_lshl_add_u64 v[162:163], v[230:231], 0, s[10:11]
	s_addc_u32 s31, s31, 0
	s_add_i32 s34, s63, s38
	global_load_lds_dwordx4 v[162:163], off nt
	v_lshl_add_u64 v[162:163], s[30:31], 0, v[134:135]
	s_mov_b32 m0, s34
	s_nop 0
	global_load_lds_dwordx4 v[162:163], off nt
	v_lshl_add_u64 v[162:163], s[30:31], 0, v[130:131]
	s_add_i32 m0, s34, 0x2000
	s_nop 0
	global_load_lds_dwordx4 v[162:163], off nt
	v_lshl_add_u64 v[162:163], v[232:233], 0, s[10:11]
	s_mov_b32 m0, s43
	s_nop 0
	global_load_lds_dwordx4 v[162:163], off
	v_lshl_add_u64 v[162:163], v[234:235], 0, s[10:11]
	s_mov_b32 m0, s44
	s_nop 0
	global_load_lds_dwordx4 v[162:163], off
	s_waitcnt vmcnt(8)
	s_waitcnt lgkmcnt(0)
	s_barrier
	s_setprio 1
	s_waitcnt lgkmcnt(0)
	v_mfma_i32_16x16x64_i8 v[62:65], v[146:149], v[198:201], v[62:65]
	v_mfma_i32_16x16x64_i8 v[54:57], v[154:157], v[198:201], v[54:57]
	v_mfma_i32_16x16x64_i8 v[46:49], v[146:149], v[206:209], v[46:49]
	v_mfma_i32_16x16x64_i8 v[38:41], v[154:157], v[206:209], v[38:41]
	v_mfma_i32_16x16x64_i8 v[30:33], v[146:149], v[214:217], v[30:33]
	v_mfma_i32_16x16x64_i8 v[22:25], v[154:157], v[214:217], v[22:25]
	v_mfma_i32_16x16x64_i8 v[14:17], v[146:149], v[222:225], v[14:17]
	v_mfma_i32_16x16x64_i8 v[6:9], v[154:157], v[222:225], v[6:9]
	v_mfma_i32_16x16x64_i8 v[62:65], v[150:153], v[202:205], v[62:65]
	v_mfma_i32_16x16x64_i8 v[54:57], v[158:161], v[202:205], v[54:57]
	v_mfma_i32_16x16x64_i8 v[46:49], v[150:153], v[210:213], v[46:49]
	v_mfma_i32_16x16x64_i8 v[38:41], v[158:161], v[210:213], v[38:41]
	v_mfma_i32_16x16x64_i8 v[30:33], v[150:153], v[218:221], v[30:33]
	v_mfma_i32_16x16x64_i8 v[22:25], v[158:161], v[218:221], v[22:25]
	v_mfma_i32_16x16x64_i8 v[14:17], v[150:153], v[226:229], v[14:17]
	v_mfma_i32_16x16x64_i8 v[6:9], v[158:161], v[226:229], v[6:9]
	s_setprio 0
	s_setprio 1
	v_mfma_i32_16x16x64_i8 v[58:61], v[182:185], v[198:201], v[58:61]
	v_mfma_i32_16x16x64_i8 v[50:53], v[190:193], v[198:201], v[50:53]
	v_mfma_i32_16x16x64_i8 v[42:45], v[182:185], v[206:209], v[42:45]
	v_mfma_i32_16x16x64_i8 v[34:37], v[190:193], v[206:209], v[34:37]
	v_mfma_i32_16x16x64_i8 v[26:29], v[182:185], v[214:217], v[26:29]
	v_mfma_i32_16x16x64_i8 v[18:21], v[190:193], v[214:217], v[18:21]
	v_mfma_i32_16x16x64_i8 v[10:13], v[182:185], v[222:225], v[10:13]
	v_mfma_i32_16x16x64_i8 v[2:5], v[190:193], v[222:225], v[2:5]
	v_mfma_i32_16x16x64_i8 v[58:61], v[186:189], v[202:205], v[58:61]
	v_mfma_i32_16x16x64_i8 v[50:53], v[194:197], v[202:205], v[50:53]
	v_mfma_i32_16x16x64_i8 v[42:45], v[186:189], v[210:213], v[42:45]
	v_mfma_i32_16x16x64_i8 v[34:37], v[194:197], v[210:213], v[34:37]
	v_mfma_i32_16x16x64_i8 v[26:29], v[186:189], v[218:221], v[26:29]
	v_mfma_i32_16x16x64_i8 v[18:21], v[194:197], v[218:221], v[18:21]
	v_mfma_i32_16x16x64_i8 v[10:13], v[186:189], v[226:229], v[10:13]
	v_mfma_i32_16x16x64_i8 v[2:5], v[194:197], v[226:229], v[2:5]
	s_setprio 0
	s_barrier
	s_add_i32 s72, s72, 2
	s_add_u32 s28, s28, 0x100
	s_addc_u32 s29, s29, 0
	s_add_u32 s70, s70, 0x100
	s_addc_u32 s71, s71, 0
	s_cmp_gt_u32 s72, 13
	s_cbranch_scc0 .LBB0_137
	s_and_b64 vcc, exec, s[14:15]
	s_cbranch_vccz .LBB0_140
	s_barrier

.LBB0_737:
	ds_read_b128 v[146:149], v178
	ds_read_b128 v[150:153], v178 offset:1024
	ds_read_b128 v[154:157], v178 offset:2048
	ds_read_b128 v[158:161], v178 offset:3072
	ds_read_b128 v[182:185], v179
	ds_read_b128 v[186:189], v179 offset:1024
	ds_read_b128 v[190:193], v179 offset:2048
	ds_read_b128 v[194:197], v179 offset:3072
	s_add_u32 s30, s28, 0xfffc0080
	s_addc_u32 s31, s29, -1
	s_cmp_eq_u32 s72, 12
	s_cselect_b32 s35, s21, s31
	s_cselect_b32 s34, s68, s30
	s_cselect_b32 s31, s19, s71
	s_cselect_b32 s30, s69, s70
	v_lshl_add_u64 v[162:163], s[28:29], 0, v[138:139]
	s_add_i32 m0, s27, 0xc000
	ds_read_b128 v[198:201], v180
	ds_read_b128 v[202:205], v180 offset:1024
	ds_read_b128 v[206:209], v180 offset:2048
	ds_read_b128 v[210:213], v180 offset:3072
	ds_read_b128 v[214:217], v180 offset:4096
	ds_read_b128 v[218:221], v180 offset:5120
	ds_read_b128 v[222:225], v180 offset:6144
	ds_read_b128 v[226:229], v180 offset:7168
	global_load_lds_dwordx4 v[162:163], off
	v_lshl_add_u64 v[162:163], s[28:29], 0, v[140:141]
	s_add_i32 m0, s27, 0xe000
	s_nop 0
	global_load_lds_dwordx4 v[162:163], off
	s_waitcnt vmcnt(8)
	s_waitcnt lgkmcnt(0)
	s_barrier
	s_setprio 1
	s_waitcnt lgkmcnt(0)
	v_mfma_i32_16x16x64_i8 v[126:129], v[146:149], v[198:201], v[126:129]
	v_mfma_i32_16x16x64_i8 v[118:121], v[154:157], v[198:201], v[118:121]
	v_mfma_i32_16x16x64_i8 v[110:113], v[146:149], v[206:209], v[110:113]
	v_mfma_i32_16x16x64_i8 v[102:105], v[154:157], v[206:209], v[102:105]
	v_mfma_i32_16x16x64_i8 v[94:97], v[146:149], v[214:217], v[94:97]
	v_mfma_i32_16x16x64_i8 v[86:89], v[154:157], v[214:217], v[86:89]
	v_mfma_i32_16x16x64_i8 v[78:81], v[146:149], v[222:225], v[78:81]
	v_mfma_i32_16x16x64_i8 v[70:73], v[154:157], v[222:225], v[70:73]
	v_mfma_i32_16x16x64_i8 v[126:129], v[150:153], v[202:205], v[126:129]
	v_mfma_i32_16x16x64_i8 v[118:121], v[158:161], v[202:205], v[118:121]
	v_mfma_i32_16x16x64_i8 v[110:113], v[150:153], v[210:213], v[110:113]
	v_mfma_i32_16x16x64_i8 v[102:105], v[158:161], v[210:213], v[102:105]
	v_mfma_i32_16x16x64_i8 v[94:97], v[150:153], v[218:221], v[94:97]
	v_mfma_i32_16x16x64_i8 v[86:89], v[158:161], v[218:221], v[86:89]
	v_mfma_i32_16x16x64_i8 v[78:81], v[150:153], v[226:229], v[78:81]
	v_mfma_i32_16x16x64_i8 v[70:73], v[158:161], v[226:229], v[70:73]
	s_setprio 0
	s_setprio 1
	v_mfma_i32_16x16x64_i8 v[122:125], v[182:185], v[198:201], v[122:125]
	v_mfma_i32_16x16x64_i8 v[114:117], v[190:193], v[198:201], v[114:117]
	v_mfma_i32_16x16x64_i8 v[106:109], v[182:185], v[206:209], v[106:109]
	v_mfma_i32_16x16x64_i8 v[98:101], v[190:193], v[206:209], v[98:101]
	v_mfma_i32_16x16x64_i8 v[90:93], v[182:185], v[214:217], v[90:93]
	v_mfma_i32_16x16x64_i8 v[82:85], v[190:193], v[214:217], v[82:85]
	v_mfma_i32_16x16x64_i8 v[74:77], v[182:185], v[222:225], v[74:77]
	v_mfma_i32_16x16x64_i8 v[66:69], v[190:193], v[222:225], v[66:69]
	v_mfma_i32_16x16x64_i8 v[122:125], v[186:189], v[202:205], v[122:125]
	v_mfma_i32_16x16x64_i8 v[114:117], v[194:197], v[202:205], v[114:117]
	v_mfma_i32_16x16x64_i8 v[106:109], v[186:189], v[210:213], v[106:109]
	v_mfma_i32_16x16x64_i8 v[98:101], v[194:197], v[210:213], v[98:101]
	v_mfma_i32_16x16x64_i8 v[90:93], v[186:189], v[218:221], v[90:93]
	v_mfma_i32_16x16x64_i8 v[82:85], v[194:197], v[218:221], v[82:85]
	v_mfma_i32_16x16x64_i8 v[74:77], v[186:189], v[226:229], v[74:77]
	v_mfma_i32_16x16x64_i8 v[66:69], v[194:197], v[226:229], v[66:69]
	s_setprio 0
	s_barrier
	s_add_i32 s73, s46, s38
	v_lshl_add_u64 v[162:163], s[30:31], 0, v[134:135]
	s_mov_b32 m0, s73
	ds_read_b128 v[198:201], v180 offset:16384
	ds_read_b128 v[202:205], v180 offset:17408
	ds_read_b128 v[206:209], v180 offset:18432
	ds_read_b128 v[210:213], v180 offset:19456
	ds_read_b128 v[214:217], v180 offset:20480
	ds_read_b128 v[218:221], v180 offset:21504
	ds_read_b128 v[222:225], v180 offset:22528
	ds_read_b128 v[226:229], v180 offset:23552
	global_load_lds_dwordx4 v[162:163], off nt
	s_add_i32 m0, s73, 0x2000
	s_add_u32 s74, s30, 0x40000
	v_lshl_add_u64 v[230:231], s[30:31], 0, v[130:131]
	s_addc_u32 s75, s31, 0
	s_add_i32 s73, s47, s38
	global_load_lds_dwordx4 v[230:231], off nt
	v_lshl_add_u64 v[232:233], s[74:75], 0, v[134:135]
	s_mov_b32 m0, s73
	v_lshl_add_u64 v[234:235], s[34:35], 0, v[132:133]
	global_load_lds_dwordx4 v[232:233], off nt
	v_lshl_add_u64 v[232:233], s[74:75], 0, v[130:131]
	s_add_i32 m0, s73, 0x2000
	s_nop 0
	global_load_lds_dwordx4 v[232:233], off nt
	v_lshl_add_u64 v[232:233], s[34:35], 0, v[136:137]
	s_mov_b32 m0, s27
	s_nop 0
	global_load_lds_dwordx4 v[232:233], off
	s_mov_b32 m0, s40
	s_nop 0
	global_load_lds_dwordx4 v[234:235], off
	s_waitcnt vmcnt(8)
	s_waitcnt lgkmcnt(0)
	s_barrier
	s_setprio 1
	s_waitcnt lgkmcnt(0)
	v_mfma_i32_16x16x64_i8 v[62:65], v[146:149], v[198:201], v[62:65]
	v_mfma_i32_16x16x64_i8 v[54:57], v[154:157], v[198:201], v[54:57]
	v_mfma_i32_16x16x64_i8 v[46:49], v[146:149], v[206:209], v[46:49]
	v_mfma_i32_16x16x64_i8 v[38:41], v[154:157], v[206:209], v[38:41]
	v_mfma_i32_16x16x64_i8 v[30:33], v[146:149], v[214:217], v[30:33]
	v_mfma_i32_16x16x64_i8 v[22:25], v[154:157], v[214:217], v[22:25]
	v_mfma_i32_16x16x64_i8 v[14:17], v[146:149], v[222:225], v[14:17]
	v_mfma_i32_16x16x64_i8 v[6:9], v[154:157], v[222:225], v[6:9]
	v_mfma_i32_16x16x64_i8 v[62:65], v[150:153], v[202:205], v[62:65]
	v_mfma_i32_16x16x64_i8 v[54:57], v[158:161], v[202:205], v[54:57]
	v_mfma_i32_16x16x64_i8 v[46:49], v[150:153], v[210:213], v[46:49]
	v_mfma_i32_16x16x64_i8 v[38:41], v[158:161], v[210:213], v[38:41]
	v_mfma_i32_16x16x64_i8 v[30:33], v[150:153], v[218:221], v[30:33]
	v_mfma_i32_16x16x64_i8 v[22:25], v[158:161], v[218:221], v[22:25]
	v_mfma_i32_16x16x64_i8 v[14:17], v[150:153], v[226:229], v[14:17]
	v_mfma_i32_16x16x64_i8 v[6:9], v[158:161], v[226:229], v[6:9]
	s_setprio 0
	s_setprio 1
	v_mfma_i32_16x16x64_i8 v[58:61], v[182:185], v[198:201], v[58:61]
	v_mfma_i32_16x16x64_i8 v[50:53], v[190:193], v[198:201], v[50:53]
	v_mfma_i32_16x16x64_i8 v[42:45], v[182:185], v[206:209], v[42:45]
	v_mfma_i32_16x16x64_i8 v[34:37], v[190:193], v[206:209], v[34:37]
	v_mfma_i32_16x16x64_i8 v[26:29], v[182:185], v[214:217], v[26:29]
	v_mfma_i32_16x16x64_i8 v[18:21], v[190:193], v[214:217], v[18:21]
	v_mfma_i32_16x16x64_i8 v[10:13], v[182:185], v[222:225], v[10:13]
	v_mfma_i32_16x16x64_i8 v[2:5], v[190:193], v[222:225], v[2:5]
	v_mfma_i32_16x16x64_i8 v[58:61], v[186:189], v[202:205], v[58:61]
	v_mfma_i32_16x16x64_i8 v[50:53], v[194:197], v[202:205], v[50:53]
	v_mfma_i32_16x16x64_i8 v[42:45], v[186:189], v[210:213], v[42:45]
	v_mfma_i32_16x16x64_i8 v[34:37], v[194:197], v[210:213], v[34:37]
	v_mfma_i32_16x16x64_i8 v[26:29], v[186:189], v[218:221], v[26:29]
	v_mfma_i32_16x16x64_i8 v[18:21], v[194:197], v[218:221], v[18:21]
	v_mfma_i32_16x16x64_i8 v[10:13], v[186:189], v[226:229], v[10:13]
	v_mfma_i32_16x16x64_i8 v[2:5], v[194:197], v[226:229], v[2:5]
	s_setprio 0
	s_barrier
	s_add_i32 s73, 0, 0x18000
	v_add_u32_e32 v158, s73, v169
	ds_read_b128 v[146:149], v158
	ds_read_b128 v[150:153], v158 offset:1024
	ds_read_b128 v[154:157], v158 offset:2048
	ds_read_b128 v[158:161], v158 offset:3072
	ds_read_b128 v[182:185], v181
	ds_read_b128 v[186:189], v181 offset:1024
	ds_read_b128 v[190:193], v181 offset:2048
	ds_read_b128 v[194:197], v181 offset:3072
	s_add_u32 s34, s34, 0x40000
	s_addc_u32 s35, s35, 0
	s_mov_b32 m0, s41
	v_lshl_add_u64 v[236:237], s[34:35], 0, v[136:137]
	ds_read_b128 v[198:201], v180 offset:32768
	ds_read_b128 v[202:205], v180 offset:33792
	ds_read_b128 v[206:209], v180 offset:34816
	ds_read_b128 v[210:213], v180 offset:35840
	ds_read_b128 v[214:217], v180 offset:36864
	ds_read_b128 v[218:221], v180 offset:37888
	ds_read_b128 v[222:225], v180 offset:38912
	ds_read_b128 v[226:229], v180 offset:39936
	global_load_lds_dwordx4 v[236:237], off
	v_lshl_add_u64 v[236:237], s[34:35], 0, v[132:133]
	s_mov_b32 m0, s42
	s_nop 0
	global_load_lds_dwordx4 v[236:237], off
	s_waitcnt vmcnt(8)
	s_waitcnt lgkmcnt(0)
	s_barrier
	s_setprio 1
	s_waitcnt lgkmcnt(0)
	v_mfma_i32_16x16x64_i8 v[126:129], v[146:149], v[198:201], v[126:129]
	v_mfma_i32_16x16x64_i8 v[118:121], v[154:157], v[198:201], v[118:121]
	v_mfma_i32_16x16x64_i8 v[110:113], v[146:149], v[206:209], v[110:113]
	v_mfma_i32_16x16x64_i8 v[102:105], v[154:157], v[206:209], v[102:105]
	v_mfma_i32_16x16x64_i8 v[94:97], v[146:149], v[214:217], v[94:97]
	v_mfma_i32_16x16x64_i8 v[86:89], v[154:157], v[214:217], v[86:89]
	v_mfma_i32_16x16x64_i8 v[78:81], v[146:149], v[222:225], v[78:81]
	v_mfma_i32_16x16x64_i8 v[70:73], v[154:157], v[222:225], v[70:73]
	v_mfma_i32_16x16x64_i8 v[126:129], v[150:153], v[202:205], v[126:129]
	v_mfma_i32_16x16x64_i8 v[118:121], v[158:161], v[202:205], v[118:121]
	v_mfma_i32_16x16x64_i8 v[110:113], v[150:153], v[210:213], v[110:113]
	v_mfma_i32_16x16x64_i8 v[102:105], v[158:161], v[210:213], v[102:105]
	v_mfma_i32_16x16x64_i8 v[94:97], v[150:153], v[218:221], v[94:97]
	v_mfma_i32_16x16x64_i8 v[86:89], v[158:161], v[218:221], v[86:89]
	v_mfma_i32_16x16x64_i8 v[78:81], v[150:153], v[226:229], v[78:81]
	v_mfma_i32_16x16x64_i8 v[70:73], v[158:161], v[226:229], v[70:73]
	s_setprio 0
	s_setprio 1
	v_mfma_i32_16x16x64_i8 v[122:125], v[182:185], v[198:201], v[122:125]
	v_mfma_i32_16x16x64_i8 v[114:117], v[190:193], v[198:201], v[114:117]
	v_mfma_i32_16x16x64_i8 v[106:109], v[182:185], v[206:209], v[106:109]
	v_mfma_i32_16x16x64_i8 v[98:101], v[190:193], v[206:209], v[98:101]
	v_mfma_i32_16x16x64_i8 v[90:93], v[182:185], v[214:217], v[90:93]
	v_mfma_i32_16x16x64_i8 v[82:85], v[190:193], v[214:217], v[82:85]
	v_mfma_i32_16x16x64_i8 v[74:77], v[182:185], v[222:225], v[74:77]
	v_mfma_i32_16x16x64_i8 v[66:69], v[190:193], v[222:225], v[66:69]
	v_mfma_i32_16x16x64_i8 v[122:125], v[186:189], v[202:205], v[122:125]
	v_mfma_i32_16x16x64_i8 v[114:117], v[194:197], v[202:205], v[114:117]
	v_mfma_i32_16x16x64_i8 v[106:109], v[186:189], v[210:213], v[106:109]
	v_mfma_i32_16x16x64_i8 v[98:101], v[194:197], v[210:213], v[98:101]
	v_mfma_i32_16x16x64_i8 v[90:93], v[186:189], v[218:221], v[90:93]
	v_mfma_i32_16x16x64_i8 v[82:85], v[194:197], v[218:221], v[82:85]
	v_mfma_i32_16x16x64_i8 v[74:77], v[186:189], v[226:229], v[74:77]
	v_mfma_i32_16x16x64_i8 v[66:69], v[194:197], v[226:229], v[66:69]
	s_setprio 0
	s_barrier
	s_add_i32 s34, s73, s38
	v_lshl_add_u64 v[162:163], v[162:163], 0, s[10:11]
	s_mov_b32 m0, s34
	ds_read_b128 v[198:201], v180 offset:49152
	ds_read_b128 v[202:205], v180 offset:50176
	ds_read_b128 v[206:209], v180 offset:51200
	ds_read_b128 v[210:213], v180 offset:52224
	ds_read_b128 v[214:217], v180 offset:53248
	ds_read_b128 v[218:221], v180 offset:54272
	ds_read_b128 v[222:225], v180 offset:55296
	ds_read_b128 v[226:229], v180 offset:56320
	global_load_lds_dwordx4 v[162:163], off nt
	s_add_i32 m0, s34, 0x2000
	s_add_u32 s30, s30, 0x40080
	v_lshl_add_u64 v[162:163], v[230:231], 0, s[10:11]
	s_addc_u32 s31, s31, 0
	s_add_i32 s34, s48, s38
	global_load_lds_dwordx4 v[162:163], off nt
	v_lshl_add_u64 v[162:163], s[30:31], 0, v[134:135]
	s_mov_b32 m0, s34
	s_nop 0
	global_load_lds_dwordx4 v[162:163], off nt
	v_lshl_add_u64 v[162:163], s[30:31], 0, v[130:131]
	s_add_i32 m0, s34, 0x2000
	s_nop 0
	global_load_lds_dwordx4 v[162:163], off nt
	v_lshl_add_u64 v[162:163], v[232:233], 0, s[10:11]
	s_mov_b32 m0, s43
	s_nop 0
	global_load_lds_dwordx4 v[162:163], off
	v_lshl_add_u64 v[162:163], v[234:235], 0, s[10:11]
	s_mov_b32 m0, s44
	s_nop 0
	global_load_lds_dwordx4 v[162:163], off
	s_waitcnt vmcnt(8)
	s_waitcnt lgkmcnt(0)
	s_barrier
	s_setprio 1
	s_waitcnt lgkmcnt(0)
	v_mfma_i32_16x16x64_i8 v[62:65], v[146:149], v[198:201], v[62:65]
	v_mfma_i32_16x16x64_i8 v[54:57], v[154:157], v[198:201], v[54:57]
	v_mfma_i32_16x16x64_i8 v[46:49], v[146:149], v[206:209], v[46:49]
	v_mfma_i32_16x16x64_i8 v[38:41], v[154:157], v[206:209], v[38:41]
	v_mfma_i32_16x16x64_i8 v[30:33], v[146:149], v[214:217], v[30:33]
	v_mfma_i32_16x16x64_i8 v[22:25], v[154:157], v[214:217], v[22:25]
	v_mfma_i32_16x16x64_i8 v[14:17], v[146:149], v[222:225], v[14:17]
	v_mfma_i32_16x16x64_i8 v[6:9], v[154:157], v[222:225], v[6:9]
	v_mfma_i32_16x16x64_i8 v[62:65], v[150:153], v[202:205], v[62:65]
	v_mfma_i32_16x16x64_i8 v[54:57], v[158:161], v[202:205], v[54:57]
	v_mfma_i32_16x16x64_i8 v[46:49], v[150:153], v[210:213], v[46:49]
	v_mfma_i32_16x16x64_i8 v[38:41], v[158:161], v[210:213], v[38:41]
	v_mfma_i32_16x16x64_i8 v[30:33], v[150:153], v[218:221], v[30:33]
	v_mfma_i32_16x16x64_i8 v[22:25], v[158:161], v[218:221], v[22:25]
	v_mfma_i32_16x16x64_i8 v[14:17], v[150:153], v[226:229], v[14:17]
	v_mfma_i32_16x16x64_i8 v[6:9], v[158:161], v[226:229], v[6:9]
	s_setprio 0
	s_setprio 1
	v_mfma_i32_16x16x64_i8 v[58:61], v[182:185], v[198:201], v[58:61]
	v_mfma_i32_16x16x64_i8 v[50:53], v[190:193], v[198:201], v[50:53]
	v_mfma_i32_16x16x64_i8 v[42:45], v[182:185], v[206:209], v[42:45]
	v_mfma_i32_16x16x64_i8 v[34:37], v[190:193], v[206:209], v[34:37]
	v_mfma_i32_16x16x64_i8 v[26:29], v[182:185], v[214:217], v[26:29]
	v_mfma_i32_16x16x64_i8 v[18:21], v[190:193], v[214:217], v[18:21]
	v_mfma_i32_16x16x64_i8 v[10:13], v[182:185], v[222:225], v[10:13]
	v_mfma_i32_16x16x64_i8 v[2:5], v[190:193], v[222:225], v[2:5]
	v_mfma_i32_16x16x64_i8 v[58:61], v[186:189], v[202:205], v[58:61]
	v_mfma_i32_16x16x64_i8 v[50:53], v[194:197], v[202:205], v[50:53]
	v_mfma_i32_16x16x64_i8 v[42:45], v[186:189], v[210:213], v[42:45]
	v_mfma_i32_16x16x64_i8 v[34:37], v[194:197], v[210:213], v[34:37]
	v_mfma_i32_16x16x64_i8 v[26:29], v[186:189], v[218:221], v[26:29]
	v_mfma_i32_16x16x64_i8 v[18:21], v[194:197], v[218:221], v[18:21]
	v_mfma_i32_16x16x64_i8 v[10:13], v[186:189], v[226:229], v[10:13]
	v_mfma_i32_16x16x64_i8 v[2:5], v[194:197], v[226:229], v[2:5]
	s_setprio 0
	s_barrier
	s_add_i32 s72, s72, 2
	s_add_u32 s28, s28, 0x100
	s_addc_u32 s29, s29, 0
	s_add_u32 s70, s70, 0x100
	s_addc_u32 s71, s71, 0
	s_cmp_gt_u32 s72, 13
	s_cbranch_scc0 .LBB0_737
	s_and_b64 vcc, exec, s[14:15]
	s_cbranch_vccz .LBB0_740
	s_barrier

.LBB0_1595:
	ds_read_b128 v[146:149], v178
	ds_read_b128 v[150:153], v178 offset:1024
	ds_read_b128 v[154:157], v178 offset:2048
	ds_read_b128 v[158:161], v178 offset:3072
	ds_read_b128 v[182:185], v179
	ds_read_b128 v[186:189], v179 offset:1024
	ds_read_b128 v[190:193], v179 offset:2048
	ds_read_b128 v[194:197], v179 offset:3072
	s_add_u32 s34, s30, 0xfffc0080
	s_addc_u32 s35, s31, -1
	s_cmp_eq_u32 s72, 12
	s_cselect_b32 s37, s23, s35
	s_cselect_b32 s36, s68, s34
	s_cselect_b32 s35, s21, s71
	s_cselect_b32 s34, s69, s70
	v_lshl_add_u64 v[162:163], s[30:31], 0, v[138:139]
	s_add_i32 m0, s29, 0xc000
	ds_read_b128 v[198:201], v180
	ds_read_b128 v[202:205], v180 offset:1024
	ds_read_b128 v[206:209], v180 offset:2048
	ds_read_b128 v[210:213], v180 offset:3072
	ds_read_b128 v[214:217], v180 offset:4096
	ds_read_b128 v[218:221], v180 offset:5120
	ds_read_b128 v[222:225], v180 offset:6144
	ds_read_b128 v[226:229], v180 offset:7168
	global_load_lds_dwordx4 v[162:163], off
	v_lshl_add_u64 v[162:163], s[30:31], 0, v[140:141]
	s_add_i32 m0, s29, 0xe000
	s_nop 0
	global_load_lds_dwordx4 v[162:163], off
	s_waitcnt vmcnt(8)
	s_waitcnt lgkmcnt(0)
	s_barrier
	s_setprio 1
	s_waitcnt lgkmcnt(0)
	v_mfma_i32_16x16x64_i8 v[126:129], v[146:149], v[198:201], v[126:129]
	v_mfma_i32_16x16x64_i8 v[118:121], v[154:157], v[198:201], v[118:121]
	v_mfma_i32_16x16x64_i8 v[110:113], v[146:149], v[206:209], v[110:113]
	v_mfma_i32_16x16x64_i8 v[102:105], v[154:157], v[206:209], v[102:105]
	v_mfma_i32_16x16x64_i8 v[94:97], v[146:149], v[214:217], v[94:97]
	v_mfma_i32_16x16x64_i8 v[86:89], v[154:157], v[214:217], v[86:89]
	v_mfma_i32_16x16x64_i8 v[78:81], v[146:149], v[222:225], v[78:81]
	v_mfma_i32_16x16x64_i8 v[70:73], v[154:157], v[222:225], v[70:73]
	v_mfma_i32_16x16x64_i8 v[126:129], v[150:153], v[202:205], v[126:129]
	v_mfma_i32_16x16x64_i8 v[118:121], v[158:161], v[202:205], v[118:121]
	v_mfma_i32_16x16x64_i8 v[110:113], v[150:153], v[210:213], v[110:113]
	v_mfma_i32_16x16x64_i8 v[102:105], v[158:161], v[210:213], v[102:105]
	v_mfma_i32_16x16x64_i8 v[94:97], v[150:153], v[218:221], v[94:97]
	v_mfma_i32_16x16x64_i8 v[86:89], v[158:161], v[218:221], v[86:89]
	v_mfma_i32_16x16x64_i8 v[78:81], v[150:153], v[226:229], v[78:81]
	v_mfma_i32_16x16x64_i8 v[70:73], v[158:161], v[226:229], v[70:73]
	s_setprio 0
	s_setprio 1
	v_mfma_i32_16x16x64_i8 v[122:125], v[182:185], v[198:201], v[122:125]
	v_mfma_i32_16x16x64_i8 v[114:117], v[190:193], v[198:201], v[114:117]
	v_mfma_i32_16x16x64_i8 v[106:109], v[182:185], v[206:209], v[106:109]
	v_mfma_i32_16x16x64_i8 v[98:101], v[190:193], v[206:209], v[98:101]
	v_mfma_i32_16x16x64_i8 v[90:93], v[182:185], v[214:217], v[90:93]
	v_mfma_i32_16x16x64_i8 v[82:85], v[190:193], v[214:217], v[82:85]
	v_mfma_i32_16x16x64_i8 v[74:77], v[182:185], v[222:225], v[74:77]
	v_mfma_i32_16x16x64_i8 v[66:69], v[190:193], v[222:225], v[66:69]
	v_mfma_i32_16x16x64_i8 v[122:125], v[186:189], v[202:205], v[122:125]
	v_mfma_i32_16x16x64_i8 v[114:117], v[194:197], v[202:205], v[114:117]
	v_mfma_i32_16x16x64_i8 v[106:109], v[186:189], v[210:213], v[106:109]
	v_mfma_i32_16x16x64_i8 v[98:101], v[194:197], v[210:213], v[98:101]
	v_mfma_i32_16x16x64_i8 v[90:93], v[186:189], v[218:221], v[90:93]
	v_mfma_i32_16x16x64_i8 v[82:85], v[194:197], v[218:221], v[82:85]
	v_mfma_i32_16x16x64_i8 v[74:77], v[186:189], v[226:229], v[74:77]
	v_mfma_i32_16x16x64_i8 v[66:69], v[194:197], v[226:229], v[66:69]
	s_setprio 0
	s_barrier
	s_add_i32 s73, s48, s40
	v_lshl_add_u64 v[162:163], s[34:35], 0, v[134:135]
	s_mov_b32 m0, s73
	ds_read_b128 v[198:201], v180 offset:16384
	ds_read_b128 v[202:205], v180 offset:17408
	ds_read_b128 v[206:209], v180 offset:18432
	ds_read_b128 v[210:213], v180 offset:19456
	ds_read_b128 v[214:217], v180 offset:20480
	ds_read_b128 v[218:221], v180 offset:21504
	ds_read_b128 v[222:225], v180 offset:22528
	ds_read_b128 v[226:229], v180 offset:23552
	global_load_lds_dwordx4 v[162:163], off nt
	s_add_i32 m0, s73, 0x2000
	s_add_u32 s74, s34, 0x40000
	v_lshl_add_u64 v[230:231], s[34:35], 0, v[130:131]
	s_addc_u32 s75, s35, 0
	s_add_i32 s73, s49, s40
	global_load_lds_dwordx4 v[230:231], off nt
	v_lshl_add_u64 v[232:233], s[74:75], 0, v[134:135]
	s_mov_b32 m0, s73
	v_lshl_add_u64 v[234:235], s[36:37], 0, v[132:133]
	global_load_lds_dwordx4 v[232:233], off nt
	v_lshl_add_u64 v[232:233], s[74:75], 0, v[130:131]
	s_add_i32 m0, s73, 0x2000
	s_nop 0
	global_load_lds_dwordx4 v[232:233], off nt
	v_lshl_add_u64 v[232:233], s[36:37], 0, v[136:137]
	s_mov_b32 m0, s29
	s_nop 0
	global_load_lds_dwordx4 v[232:233], off
	s_mov_b32 m0, s42
	s_nop 0
	global_load_lds_dwordx4 v[234:235], off
	s_waitcnt vmcnt(8)
	s_waitcnt lgkmcnt(0)
	s_barrier
	s_setprio 1
	s_waitcnt lgkmcnt(0)
	v_mfma_i32_16x16x64_i8 v[62:65], v[146:149], v[198:201], v[62:65]
	v_mfma_i32_16x16x64_i8 v[54:57], v[154:157], v[198:201], v[54:57]
	v_mfma_i32_16x16x64_i8 v[46:49], v[146:149], v[206:209], v[46:49]
	v_mfma_i32_16x16x64_i8 v[38:41], v[154:157], v[206:209], v[38:41]
	v_mfma_i32_16x16x64_i8 v[30:33], v[146:149], v[214:217], v[30:33]
	v_mfma_i32_16x16x64_i8 v[22:25], v[154:157], v[214:217], v[22:25]
	v_mfma_i32_16x16x64_i8 v[14:17], v[146:149], v[222:225], v[14:17]
	v_mfma_i32_16x16x64_i8 v[6:9], v[154:157], v[222:225], v[6:9]
	v_mfma_i32_16x16x64_i8 v[62:65], v[150:153], v[202:205], v[62:65]
	v_mfma_i32_16x16x64_i8 v[54:57], v[158:161], v[202:205], v[54:57]
	v_mfma_i32_16x16x64_i8 v[46:49], v[150:153], v[210:213], v[46:49]
	v_mfma_i32_16x16x64_i8 v[38:41], v[158:161], v[210:213], v[38:41]
	v_mfma_i32_16x16x64_i8 v[30:33], v[150:153], v[218:221], v[30:33]
	v_mfma_i32_16x16x64_i8 v[22:25], v[158:161], v[218:221], v[22:25]
	v_mfma_i32_16x16x64_i8 v[14:17], v[150:153], v[226:229], v[14:17]
	v_mfma_i32_16x16x64_i8 v[6:9], v[158:161], v[226:229], v[6:9]
	s_setprio 0
	s_setprio 1
	v_mfma_i32_16x16x64_i8 v[58:61], v[182:185], v[198:201], v[58:61]
	v_mfma_i32_16x16x64_i8 v[50:53], v[190:193], v[198:201], v[50:53]
	v_mfma_i32_16x16x64_i8 v[42:45], v[182:185], v[206:209], v[42:45]
	v_mfma_i32_16x16x64_i8 v[34:37], v[190:193], v[206:209], v[34:37]
	v_mfma_i32_16x16x64_i8 v[26:29], v[182:185], v[214:217], v[26:29]
	v_mfma_i32_16x16x64_i8 v[18:21], v[190:193], v[214:217], v[18:21]
	v_mfma_i32_16x16x64_i8 v[10:13], v[182:185], v[222:225], v[10:13]
	v_mfma_i32_16x16x64_i8 v[2:5], v[190:193], v[222:225], v[2:5]
	v_mfma_i32_16x16x64_i8 v[58:61], v[186:189], v[202:205], v[58:61]
	v_mfma_i32_16x16x64_i8 v[50:53], v[194:197], v[202:205], v[50:53]
	v_mfma_i32_16x16x64_i8 v[42:45], v[186:189], v[210:213], v[42:45]
	v_mfma_i32_16x16x64_i8 v[34:37], v[194:197], v[210:213], v[34:37]
	v_mfma_i32_16x16x64_i8 v[26:29], v[186:189], v[218:221], v[26:29]
	v_mfma_i32_16x16x64_i8 v[18:21], v[194:197], v[218:221], v[18:21]
	v_mfma_i32_16x16x64_i8 v[10:13], v[186:189], v[226:229], v[10:13]
	v_mfma_i32_16x16x64_i8 v[2:5], v[194:197], v[226:229], v[2:5]
	s_setprio 0
	s_barrier
	s_add_i32 s73, 0, 0x18000
	v_add_u32_e32 v158, s73, v169
	ds_read_b128 v[146:149], v158
	ds_read_b128 v[150:153], v158 offset:1024
	ds_read_b128 v[154:157], v158 offset:2048
	ds_read_b128 v[158:161], v158 offset:3072
	ds_read_b128 v[182:185], v181
	ds_read_b128 v[186:189], v181 offset:1024
	ds_read_b128 v[190:193], v181 offset:2048
	ds_read_b128 v[194:197], v181 offset:3072
	s_add_u32 s36, s36, 0x40000
	s_addc_u32 s37, s37, 0
	s_mov_b32 m0, s43
	v_lshl_add_u64 v[236:237], s[36:37], 0, v[136:137]
	ds_read_b128 v[198:201], v180 offset:32768
	ds_read_b128 v[202:205], v180 offset:33792
	ds_read_b128 v[206:209], v180 offset:34816
	ds_read_b128 v[210:213], v180 offset:35840
	ds_read_b128 v[214:217], v180 offset:36864
	ds_read_b128 v[218:221], v180 offset:37888
	ds_read_b128 v[222:225], v180 offset:38912
	ds_read_b128 v[226:229], v180 offset:39936
	global_load_lds_dwordx4 v[236:237], off
	v_lshl_add_u64 v[236:237], s[36:37], 0, v[132:133]
	s_mov_b32 m0, s44
	s_nop 0
	global_load_lds_dwordx4 v[236:237], off
	s_waitcnt vmcnt(8)
	s_waitcnt lgkmcnt(0)
	s_barrier
	s_setprio 1
	s_waitcnt lgkmcnt(0)
	v_mfma_i32_16x16x64_i8 v[126:129], v[146:149], v[198:201], v[126:129]
	v_mfma_i32_16x16x64_i8 v[118:121], v[154:157], v[198:201], v[118:121]
	v_mfma_i32_16x16x64_i8 v[110:113], v[146:149], v[206:209], v[110:113]
	v_mfma_i32_16x16x64_i8 v[102:105], v[154:157], v[206:209], v[102:105]
	v_mfma_i32_16x16x64_i8 v[94:97], v[146:149], v[214:217], v[94:97]
	v_mfma_i32_16x16x64_i8 v[86:89], v[154:157], v[214:217], v[86:89]
	v_mfma_i32_16x16x64_i8 v[78:81], v[146:149], v[222:225], v[78:81]
	v_mfma_i32_16x16x64_i8 v[70:73], v[154:157], v[222:225], v[70:73]
	v_mfma_i32_16x16x64_i8 v[126:129], v[150:153], v[202:205], v[126:129]
	v_mfma_i32_16x16x64_i8 v[118:121], v[158:161], v[202:205], v[118:121]
	v_mfma_i32_16x16x64_i8 v[110:113], v[150:153], v[210:213], v[110:113]
	v_mfma_i32_16x16x64_i8 v[102:105], v[158:161], v[210:213], v[102:105]
	v_mfma_i32_16x16x64_i8 v[94:97], v[150:153], v[218:221], v[94:97]
	v_mfma_i32_16x16x64_i8 v[86:89], v[158:161], v[218:221], v[86:89]
	v_mfma_i32_16x16x64_i8 v[78:81], v[150:153], v[226:229], v[78:81]
	v_mfma_i32_16x16x64_i8 v[70:73], v[158:161], v[226:229], v[70:73]
	s_setprio 0
	s_setprio 1
	v_mfma_i32_16x16x64_i8 v[122:125], v[182:185], v[198:201], v[122:125]
	v_mfma_i32_16x16x64_i8 v[114:117], v[190:193], v[198:201], v[114:117]
	v_mfma_i32_16x16x64_i8 v[106:109], v[182:185], v[206:209], v[106:109]
	v_mfma_i32_16x16x64_i8 v[98:101], v[190:193], v[206:209], v[98:101]
	v_mfma_i32_16x16x64_i8 v[90:93], v[182:185], v[214:217], v[90:93]
	v_mfma_i32_16x16x64_i8 v[82:85], v[190:193], v[214:217], v[82:85]
	v_mfma_i32_16x16x64_i8 v[74:77], v[182:185], v[222:225], v[74:77]
	v_mfma_i32_16x16x64_i8 v[66:69], v[190:193], v[222:225], v[66:69]
	v_mfma_i32_16x16x64_i8 v[122:125], v[186:189], v[202:205], v[122:125]
	v_mfma_i32_16x16x64_i8 v[114:117], v[194:197], v[202:205], v[114:117]
	v_mfma_i32_16x16x64_i8 v[106:109], v[186:189], v[210:213], v[106:109]
	v_mfma_i32_16x16x64_i8 v[98:101], v[194:197], v[210:213], v[98:101]
	v_mfma_i32_16x16x64_i8 v[90:93], v[186:189], v[218:221], v[90:93]
	v_mfma_i32_16x16x64_i8 v[82:85], v[194:197], v[218:221], v[82:85]
	v_mfma_i32_16x16x64_i8 v[74:77], v[186:189], v[226:229], v[74:77]
	v_mfma_i32_16x16x64_i8 v[66:69], v[194:197], v[226:229], v[66:69]
	s_setprio 0
	s_barrier
	s_add_i32 s36, s73, s40
	v_lshl_add_u64 v[162:163], v[162:163], 0, s[10:11]
	s_mov_b32 m0, s36
	ds_read_b128 v[198:201], v180 offset:49152
	ds_read_b128 v[202:205], v180 offset:50176
	ds_read_b128 v[206:209], v180 offset:51200
	ds_read_b128 v[210:213], v180 offset:52224
	ds_read_b128 v[214:217], v180 offset:53248
	ds_read_b128 v[218:221], v180 offset:54272
	ds_read_b128 v[222:225], v180 offset:55296
	ds_read_b128 v[226:229], v180 offset:56320
	global_load_lds_dwordx4 v[162:163], off nt
	s_add_i32 m0, s36, 0x2000
	s_add_u32 s34, s34, 0x40080
	v_lshl_add_u64 v[162:163], v[230:231], 0, s[10:11]
	s_addc_u32 s35, s35, 0
	s_add_i32 s36, s50, s40
	global_load_lds_dwordx4 v[162:163], off nt
	v_lshl_add_u64 v[162:163], s[34:35], 0, v[134:135]
	s_mov_b32 m0, s36
	s_nop 0
	global_load_lds_dwordx4 v[162:163], off nt
	v_lshl_add_u64 v[162:163], s[34:35], 0, v[130:131]
	s_add_i32 m0, s36, 0x2000
	s_nop 0
	global_load_lds_dwordx4 v[162:163], off nt
	v_lshl_add_u64 v[162:163], v[232:233], 0, s[10:11]
	s_mov_b32 m0, s45
	s_nop 0
	global_load_lds_dwordx4 v[162:163], off
	v_lshl_add_u64 v[162:163], v[234:235], 0, s[10:11]
	s_mov_b32 m0, s46
	s_nop 0
	global_load_lds_dwordx4 v[162:163], off
	s_waitcnt vmcnt(8)
	s_waitcnt lgkmcnt(0)
	s_barrier
	s_setprio 1
	s_waitcnt lgkmcnt(0)
	v_mfma_i32_16x16x64_i8 v[62:65], v[146:149], v[198:201], v[62:65]
	v_mfma_i32_16x16x64_i8 v[54:57], v[154:157], v[198:201], v[54:57]
	v_mfma_i32_16x16x64_i8 v[46:49], v[146:149], v[206:209], v[46:49]
	v_mfma_i32_16x16x64_i8 v[38:41], v[154:157], v[206:209], v[38:41]
	v_mfma_i32_16x16x64_i8 v[30:33], v[146:149], v[214:217], v[30:33]
	v_mfma_i32_16x16x64_i8 v[22:25], v[154:157], v[214:217], v[22:25]
	v_mfma_i32_16x16x64_i8 v[14:17], v[146:149], v[222:225], v[14:17]
	v_mfma_i32_16x16x64_i8 v[6:9], v[154:157], v[222:225], v[6:9]
	v_mfma_i32_16x16x64_i8 v[62:65], v[150:153], v[202:205], v[62:65]
	v_mfma_i32_16x16x64_i8 v[54:57], v[158:161], v[202:205], v[54:57]
	v_mfma_i32_16x16x64_i8 v[46:49], v[150:153], v[210:213], v[46:49]
	v_mfma_i32_16x16x64_i8 v[38:41], v[158:161], v[210:213], v[38:41]
	v_mfma_i32_16x16x64_i8 v[30:33], v[150:153], v[218:221], v[30:33]
	v_mfma_i32_16x16x64_i8 v[22:25], v[158:161], v[218:221], v[22:25]
	v_mfma_i32_16x16x64_i8 v[14:17], v[150:153], v[226:229], v[14:17]
	v_mfma_i32_16x16x64_i8 v[6:9], v[158:161], v[226:229], v[6:9]
	s_setprio 0
	s_setprio 1
	v_mfma_i32_16x16x64_i8 v[58:61], v[182:185], v[198:201], v[58:61]
	v_mfma_i32_16x16x64_i8 v[50:53], v[190:193], v[198:201], v[50:53]
	v_mfma_i32_16x16x64_i8 v[42:45], v[182:185], v[206:209], v[42:45]
	v_mfma_i32_16x16x64_i8 v[34:37], v[190:193], v[206:209], v[34:37]
	v_mfma_i32_16x16x64_i8 v[26:29], v[182:185], v[214:217], v[26:29]
	v_mfma_i32_16x16x64_i8 v[18:21], v[190:193], v[214:217], v[18:21]
	v_mfma_i32_16x16x64_i8 v[10:13], v[182:185], v[222:225], v[10:13]
	v_mfma_i32_16x16x64_i8 v[2:5], v[190:193], v[222:225], v[2:5]
	v_mfma_i32_16x16x64_i8 v[58:61], v[186:189], v[202:205], v[58:61]
	v_mfma_i32_16x16x64_i8 v[50:53], v[194:197], v[202:205], v[50:53]
	v_mfma_i32_16x16x64_i8 v[42:45], v[186:189], v[210:213], v[42:45]
	v_mfma_i32_16x16x64_i8 v[34:37], v[194:197], v[210:213], v[34:37]
	v_mfma_i32_16x16x64_i8 v[26:29], v[186:189], v[218:221], v[26:29]
	v_mfma_i32_16x16x64_i8 v[18:21], v[194:197], v[218:221], v[18:21]
	v_mfma_i32_16x16x64_i8 v[10:13], v[186:189], v[226:229], v[10:13]
	v_mfma_i32_16x16x64_i8 v[2:5], v[194:197], v[226:229], v[2:5]
	s_setprio 0
	s_barrier
	s_add_i32 s72, s72, 2
	s_add_u32 s30, s30, 0x100
	s_addc_u32 s31, s31, 0
	s_add_u32 s70, s70, 0x100
	s_addc_u32 s71, s71, 0
	s_cmp_gt_u32 s72, 13
	s_cbranch_scc0 .LBB0_1595
	s_and_b64 vcc, exec, s[14:15]
	s_cbranch_vccz .LBB0_1598
	s_barrier

.LBB0_2470:
	ds_read_b128 v[146:149], v178
	ds_read_b128 v[150:153], v178 offset:1024
	ds_read_b128 v[154:157], v178 offset:2048
	ds_read_b128 v[158:161], v178 offset:3072
	ds_read_b128 v[182:185], v179
	ds_read_b128 v[186:189], v179 offset:1024
	ds_read_b128 v[190:193], v179 offset:2048
	ds_read_b128 v[194:197], v179 offset:3072
	s_add_u32 s30, s28, 0xfffc0080
	s_addc_u32 s31, s29, -1
	s_cmp_eq_u32 s57, 12
	s_cselect_b32 s35, s21, s31
	s_cselect_b32 s34, s53, s30
	s_cselect_b32 s31, s17, s56
	s_cselect_b32 s30, s54, s55
	v_lshl_add_u64 v[162:163], s[28:29], 0, v[138:139]
	s_add_i32 m0, s27, 0xc000
	ds_read_b128 v[198:201], v180
	ds_read_b128 v[202:205], v180 offset:1024
	ds_read_b128 v[206:209], v180 offset:2048
	ds_read_b128 v[210:213], v180 offset:3072
	ds_read_b128 v[214:217], v180 offset:4096
	ds_read_b128 v[218:221], v180 offset:5120
	ds_read_b128 v[222:225], v180 offset:6144
	ds_read_b128 v[226:229], v180 offset:7168
	global_load_lds_dwordx4 v[162:163], off
	v_lshl_add_u64 v[162:163], s[28:29], 0, v[140:141]
	s_add_i32 m0, s27, 0xe000
	s_nop 0
	global_load_lds_dwordx4 v[162:163], off
	s_waitcnt vmcnt(8)
	s_waitcnt lgkmcnt(0)
	s_barrier
	s_setprio 1
	s_waitcnt lgkmcnt(0)
	v_mfma_i32_16x16x64_i8 v[126:129], v[146:149], v[198:201], v[126:129]
	v_mfma_i32_16x16x64_i8 v[118:121], v[154:157], v[198:201], v[118:121]
	v_mfma_i32_16x16x64_i8 v[110:113], v[146:149], v[206:209], v[110:113]
	v_mfma_i32_16x16x64_i8 v[102:105], v[154:157], v[206:209], v[102:105]
	v_mfma_i32_16x16x64_i8 v[94:97], v[146:149], v[214:217], v[94:97]
	v_mfma_i32_16x16x64_i8 v[86:89], v[154:157], v[214:217], v[86:89]
	v_mfma_i32_16x16x64_i8 v[78:81], v[146:149], v[222:225], v[78:81]
	v_mfma_i32_16x16x64_i8 v[70:73], v[154:157], v[222:225], v[70:73]
	v_mfma_i32_16x16x64_i8 v[126:129], v[150:153], v[202:205], v[126:129]
	v_mfma_i32_16x16x64_i8 v[118:121], v[158:161], v[202:205], v[118:121]
	v_mfma_i32_16x16x64_i8 v[110:113], v[150:153], v[210:213], v[110:113]
	v_mfma_i32_16x16x64_i8 v[102:105], v[158:161], v[210:213], v[102:105]
	v_mfma_i32_16x16x64_i8 v[94:97], v[150:153], v[218:221], v[94:97]
	v_mfma_i32_16x16x64_i8 v[86:89], v[158:161], v[218:221], v[86:89]
	v_mfma_i32_16x16x64_i8 v[78:81], v[150:153], v[226:229], v[78:81]
	v_mfma_i32_16x16x64_i8 v[70:73], v[158:161], v[226:229], v[70:73]
	s_setprio 0
	s_setprio 1
	v_mfma_i32_16x16x64_i8 v[122:125], v[182:185], v[198:201], v[122:125]
	v_mfma_i32_16x16x64_i8 v[114:117], v[190:193], v[198:201], v[114:117]
	v_mfma_i32_16x16x64_i8 v[106:109], v[182:185], v[206:209], v[106:109]
	v_mfma_i32_16x16x64_i8 v[98:101], v[190:193], v[206:209], v[98:101]
	v_mfma_i32_16x16x64_i8 v[90:93], v[182:185], v[214:217], v[90:93]
	v_mfma_i32_16x16x64_i8 v[82:85], v[190:193], v[214:217], v[82:85]
	v_mfma_i32_16x16x64_i8 v[74:77], v[182:185], v[222:225], v[74:77]
	v_mfma_i32_16x16x64_i8 v[66:69], v[190:193], v[222:225], v[66:69]
	v_mfma_i32_16x16x64_i8 v[122:125], v[186:189], v[202:205], v[122:125]
	v_mfma_i32_16x16x64_i8 v[114:117], v[194:197], v[202:205], v[114:117]
	v_mfma_i32_16x16x64_i8 v[106:109], v[186:189], v[210:213], v[106:109]
	v_mfma_i32_16x16x64_i8 v[98:101], v[194:197], v[210:213], v[98:101]
	v_mfma_i32_16x16x64_i8 v[90:93], v[186:189], v[218:221], v[90:93]
	v_mfma_i32_16x16x64_i8 v[82:85], v[194:197], v[218:221], v[82:85]
	v_mfma_i32_16x16x64_i8 v[74:77], v[186:189], v[226:229], v[74:77]
	v_mfma_i32_16x16x64_i8 v[66:69], v[194:197], v[226:229], v[66:69]
	s_setprio 0
	s_barrier
	s_add_i32 s63, s46, s38
	v_lshl_add_u64 v[162:163], s[30:31], 0, v[134:135]
	s_mov_b32 m0, s63
	ds_read_b128 v[198:201], v180 offset:16384
	ds_read_b128 v[202:205], v180 offset:17408
	ds_read_b128 v[206:209], v180 offset:18432
	ds_read_b128 v[210:213], v180 offset:19456
	ds_read_b128 v[214:217], v180 offset:20480
	ds_read_b128 v[218:221], v180 offset:21504
	ds_read_b128 v[222:225], v180 offset:22528
	ds_read_b128 v[226:229], v180 offset:23552
	global_load_lds_dwordx4 v[162:163], off nt
	s_add_i32 m0, s63, 0x2000
	s_add_u32 s68, s30, 0x40000
	v_lshl_add_u64 v[230:231], s[30:31], 0, v[130:131]
	s_addc_u32 s69, s31, 0
	s_add_i32 s63, s47, s38
	global_load_lds_dwordx4 v[230:231], off nt
	v_lshl_add_u64 v[232:233], s[68:69], 0, v[134:135]
	s_mov_b32 m0, s63
	v_lshl_add_u64 v[234:235], s[34:35], 0, v[132:133]
	global_load_lds_dwordx4 v[232:233], off nt
	v_lshl_add_u64 v[232:233], s[68:69], 0, v[130:131]
	s_add_i32 m0, s63, 0x2000
	s_nop 0
	global_load_lds_dwordx4 v[232:233], off nt
	v_lshl_add_u64 v[232:233], s[34:35], 0, v[136:137]
	s_mov_b32 m0, s27
	s_nop 0
	global_load_lds_dwordx4 v[232:233], off
	s_mov_b32 m0, s40
	s_nop 0
	global_load_lds_dwordx4 v[234:235], off
	s_waitcnt vmcnt(8)
	s_waitcnt lgkmcnt(0)
	s_barrier
	s_setprio 1
	s_waitcnt lgkmcnt(0)
	v_mfma_i32_16x16x64_i8 v[62:65], v[146:149], v[198:201], v[62:65]
	v_mfma_i32_16x16x64_i8 v[54:57], v[154:157], v[198:201], v[54:57]
	v_mfma_i32_16x16x64_i8 v[46:49], v[146:149], v[206:209], v[46:49]
	v_mfma_i32_16x16x64_i8 v[38:41], v[154:157], v[206:209], v[38:41]
	v_mfma_i32_16x16x64_i8 v[30:33], v[146:149], v[214:217], v[30:33]
	v_mfma_i32_16x16x64_i8 v[22:25], v[154:157], v[214:217], v[22:25]
	v_mfma_i32_16x16x64_i8 v[14:17], v[146:149], v[222:225], v[14:17]
	v_mfma_i32_16x16x64_i8 v[6:9], v[154:157], v[222:225], v[6:9]
	v_mfma_i32_16x16x64_i8 v[62:65], v[150:153], v[202:205], v[62:65]
	v_mfma_i32_16x16x64_i8 v[54:57], v[158:161], v[202:205], v[54:57]
	v_mfma_i32_16x16x64_i8 v[46:49], v[150:153], v[210:213], v[46:49]
	v_mfma_i32_16x16x64_i8 v[38:41], v[158:161], v[210:213], v[38:41]
	v_mfma_i32_16x16x64_i8 v[30:33], v[150:153], v[218:221], v[30:33]
	v_mfma_i32_16x16x64_i8 v[22:25], v[158:161], v[218:221], v[22:25]
	v_mfma_i32_16x16x64_i8 v[14:17], v[150:153], v[226:229], v[14:17]
	v_mfma_i32_16x16x64_i8 v[6:9], v[158:161], v[226:229], v[6:9]
	s_setprio 0
	s_setprio 1
	v_mfma_i32_16x16x64_i8 v[58:61], v[182:185], v[198:201], v[58:61]
	v_mfma_i32_16x16x64_i8 v[50:53], v[190:193], v[198:201], v[50:53]
	v_mfma_i32_16x16x64_i8 v[42:45], v[182:185], v[206:209], v[42:45]
	v_mfma_i32_16x16x64_i8 v[34:37], v[190:193], v[206:209], v[34:37]
	v_mfma_i32_16x16x64_i8 v[26:29], v[182:185], v[214:217], v[26:29]
	v_mfma_i32_16x16x64_i8 v[18:21], v[190:193], v[214:217], v[18:21]
	v_mfma_i32_16x16x64_i8 v[10:13], v[182:185], v[222:225], v[10:13]
	v_mfma_i32_16x16x64_i8 v[2:5], v[190:193], v[222:225], v[2:5]
	v_mfma_i32_16x16x64_i8 v[58:61], v[186:189], v[202:205], v[58:61]
	v_mfma_i32_16x16x64_i8 v[50:53], v[194:197], v[202:205], v[50:53]
	v_mfma_i32_16x16x64_i8 v[42:45], v[186:189], v[210:213], v[42:45]
	v_mfma_i32_16x16x64_i8 v[34:37], v[194:197], v[210:213], v[34:37]
	v_mfma_i32_16x16x64_i8 v[26:29], v[186:189], v[218:221], v[26:29]
	v_mfma_i32_16x16x64_i8 v[18:21], v[194:197], v[218:221], v[18:21]
	v_mfma_i32_16x16x64_i8 v[10:13], v[186:189], v[226:229], v[10:13]
	v_mfma_i32_16x16x64_i8 v[2:5], v[194:197], v[226:229], v[2:5]
	s_setprio 0
	s_barrier
	s_add_i32 s63, 0, 0x18000
	v_add_u32_e32 v158, s63, v169
	ds_read_b128 v[146:149], v158
	ds_read_b128 v[150:153], v158 offset:1024
	ds_read_b128 v[154:157], v158 offset:2048
	ds_read_b128 v[158:161], v158 offset:3072
	ds_read_b128 v[182:185], v181
	ds_read_b128 v[186:189], v181 offset:1024
	ds_read_b128 v[190:193], v181 offset:2048
	ds_read_b128 v[194:197], v181 offset:3072
	s_add_u32 s34, s34, 0x40000
	s_addc_u32 s35, s35, 0
	s_mov_b32 m0, s41
	v_lshl_add_u64 v[236:237], s[34:35], 0, v[136:137]
	ds_read_b128 v[198:201], v180 offset:32768
	ds_read_b128 v[202:205], v180 offset:33792
	ds_read_b128 v[206:209], v180 offset:34816
	ds_read_b128 v[210:213], v180 offset:35840
	ds_read_b128 v[214:217], v180 offset:36864
	ds_read_b128 v[218:221], v180 offset:37888
	ds_read_b128 v[222:225], v180 offset:38912
	ds_read_b128 v[226:229], v180 offset:39936
	global_load_lds_dwordx4 v[236:237], off
	v_lshl_add_u64 v[236:237], s[34:35], 0, v[132:133]
	s_mov_b32 m0, s42
	s_nop 0
	global_load_lds_dwordx4 v[236:237], off
	s_waitcnt vmcnt(8)
	s_waitcnt lgkmcnt(0)
	s_barrier
	s_setprio 1
	s_waitcnt lgkmcnt(0)
	v_mfma_i32_16x16x64_i8 v[126:129], v[146:149], v[198:201], v[126:129]
	v_mfma_i32_16x16x64_i8 v[118:121], v[154:157], v[198:201], v[118:121]
	v_mfma_i32_16x16x64_i8 v[110:113], v[146:149], v[206:209], v[110:113]
	v_mfma_i32_16x16x64_i8 v[102:105], v[154:157], v[206:209], v[102:105]
	v_mfma_i32_16x16x64_i8 v[94:97], v[146:149], v[214:217], v[94:97]
	v_mfma_i32_16x16x64_i8 v[86:89], v[154:157], v[214:217], v[86:89]
	v_mfma_i32_16x16x64_i8 v[78:81], v[146:149], v[222:225], v[78:81]
	v_mfma_i32_16x16x64_i8 v[70:73], v[154:157], v[222:225], v[70:73]
	v_mfma_i32_16x16x64_i8 v[126:129], v[150:153], v[202:205], v[126:129]
	v_mfma_i32_16x16x64_i8 v[118:121], v[158:161], v[202:205], v[118:121]
	v_mfma_i32_16x16x64_i8 v[110:113], v[150:153], v[210:213], v[110:113]
	v_mfma_i32_16x16x64_i8 v[102:105], v[158:161], v[210:213], v[102:105]
	v_mfma_i32_16x16x64_i8 v[94:97], v[150:153], v[218:221], v[94:97]
	v_mfma_i32_16x16x64_i8 v[86:89], v[158:161], v[218:221], v[86:89]
	v_mfma_i32_16x16x64_i8 v[78:81], v[150:153], v[226:229], v[78:81]
	v_mfma_i32_16x16x64_i8 v[70:73], v[158:161], v[226:229], v[70:73]
	s_setprio 0
	s_setprio 1
	v_mfma_i32_16x16x64_i8 v[122:125], v[182:185], v[198:201], v[122:125]
	v_mfma_i32_16x16x64_i8 v[114:117], v[190:193], v[198:201], v[114:117]
	v_mfma_i32_16x16x64_i8 v[106:109], v[182:185], v[206:209], v[106:109]
	v_mfma_i32_16x16x64_i8 v[98:101], v[190:193], v[206:209], v[98:101]
	v_mfma_i32_16x16x64_i8 v[90:93], v[182:185], v[214:217], v[90:93]
	v_mfma_i32_16x16x64_i8 v[82:85], v[190:193], v[214:217], v[82:85]
	v_mfma_i32_16x16x64_i8 v[74:77], v[182:185], v[222:225], v[74:77]
	v_mfma_i32_16x16x64_i8 v[66:69], v[190:193], v[222:225], v[66:69]
	v_mfma_i32_16x16x64_i8 v[122:125], v[186:189], v[202:205], v[122:125]
	v_mfma_i32_16x16x64_i8 v[114:117], v[194:197], v[202:205], v[114:117]
	v_mfma_i32_16x16x64_i8 v[106:109], v[186:189], v[210:213], v[106:109]
	v_mfma_i32_16x16x64_i8 v[98:101], v[194:197], v[210:213], v[98:101]
	v_mfma_i32_16x16x64_i8 v[90:93], v[186:189], v[218:221], v[90:93]
	v_mfma_i32_16x16x64_i8 v[82:85], v[194:197], v[218:221], v[82:85]
	v_mfma_i32_16x16x64_i8 v[74:77], v[186:189], v[226:229], v[74:77]
	v_mfma_i32_16x16x64_i8 v[66:69], v[194:197], v[226:229], v[66:69]
	s_setprio 0
	s_barrier
	s_add_i32 s34, s63, s38
	v_lshl_add_u64 v[162:163], v[162:163], 0, s[8:9]
	s_mov_b32 m0, s34
	ds_read_b128 v[198:201], v180 offset:49152
	ds_read_b128 v[202:205], v180 offset:50176
	ds_read_b128 v[206:209], v180 offset:51200
	ds_read_b128 v[210:213], v180 offset:52224
	ds_read_b128 v[214:217], v180 offset:53248
	ds_read_b128 v[218:221], v180 offset:54272
	ds_read_b128 v[222:225], v180 offset:55296
	ds_read_b128 v[226:229], v180 offset:56320
	global_load_lds_dwordx4 v[162:163], off nt
	s_add_i32 m0, s34, 0x2000
	s_add_u32 s30, s30, 0x40080
	v_lshl_add_u64 v[162:163], v[230:231], 0, s[8:9]
	s_addc_u32 s31, s31, 0
	s_add_i32 s34, s48, s38
	global_load_lds_dwordx4 v[162:163], off nt
	v_lshl_add_u64 v[162:163], s[30:31], 0, v[134:135]
	s_mov_b32 m0, s34
	s_nop 0
	global_load_lds_dwordx4 v[162:163], off nt
	v_lshl_add_u64 v[162:163], s[30:31], 0, v[130:131]
	s_add_i32 m0, s34, 0x2000
	s_nop 0
	global_load_lds_dwordx4 v[162:163], off nt
	v_lshl_add_u64 v[162:163], v[232:233], 0, s[8:9]
	s_mov_b32 m0, s43
	s_nop 0
	global_load_lds_dwordx4 v[162:163], off
	v_lshl_add_u64 v[162:163], v[234:235], 0, s[8:9]
	s_mov_b32 m0, s44
	s_nop 0
	global_load_lds_dwordx4 v[162:163], off
	s_waitcnt vmcnt(8)
	s_waitcnt lgkmcnt(0)
	s_barrier
	s_setprio 1
	s_waitcnt lgkmcnt(0)
	v_mfma_i32_16x16x64_i8 v[62:65], v[146:149], v[198:201], v[62:65]
	v_mfma_i32_16x16x64_i8 v[54:57], v[154:157], v[198:201], v[54:57]
	v_mfma_i32_16x16x64_i8 v[46:49], v[146:149], v[206:209], v[46:49]
	v_mfma_i32_16x16x64_i8 v[38:41], v[154:157], v[206:209], v[38:41]
	v_mfma_i32_16x16x64_i8 v[30:33], v[146:149], v[214:217], v[30:33]
	v_mfma_i32_16x16x64_i8 v[22:25], v[154:157], v[214:217], v[22:25]
	v_mfma_i32_16x16x64_i8 v[14:17], v[146:149], v[222:225], v[14:17]
	v_mfma_i32_16x16x64_i8 v[6:9], v[154:157], v[222:225], v[6:9]
	v_mfma_i32_16x16x64_i8 v[62:65], v[150:153], v[202:205], v[62:65]
	v_mfma_i32_16x16x64_i8 v[54:57], v[158:161], v[202:205], v[54:57]
	v_mfma_i32_16x16x64_i8 v[46:49], v[150:153], v[210:213], v[46:49]
	v_mfma_i32_16x16x64_i8 v[38:41], v[158:161], v[210:213], v[38:41]
	v_mfma_i32_16x16x64_i8 v[30:33], v[150:153], v[218:221], v[30:33]
	v_mfma_i32_16x16x64_i8 v[22:25], v[158:161], v[218:221], v[22:25]
	v_mfma_i32_16x16x64_i8 v[14:17], v[150:153], v[226:229], v[14:17]
	v_mfma_i32_16x16x64_i8 v[6:9], v[158:161], v[226:229], v[6:9]
	s_setprio 0
	s_setprio 1
	v_mfma_i32_16x16x64_i8 v[58:61], v[182:185], v[198:201], v[58:61]
	v_mfma_i32_16x16x64_i8 v[50:53], v[190:193], v[198:201], v[50:53]
	v_mfma_i32_16x16x64_i8 v[42:45], v[182:185], v[206:209], v[42:45]
	v_mfma_i32_16x16x64_i8 v[34:37], v[190:193], v[206:209], v[34:37]
	v_mfma_i32_16x16x64_i8 v[26:29], v[182:185], v[214:217], v[26:29]
	v_mfma_i32_16x16x64_i8 v[18:21], v[190:193], v[214:217], v[18:21]
	v_mfma_i32_16x16x64_i8 v[10:13], v[182:185], v[222:225], v[10:13]
	v_mfma_i32_16x16x64_i8 v[2:5], v[190:193], v[222:225], v[2:5]
	v_mfma_i32_16x16x64_i8 v[58:61], v[186:189], v[202:205], v[58:61]
	v_mfma_i32_16x16x64_i8 v[50:53], v[194:197], v[202:205], v[50:53]
	v_mfma_i32_16x16x64_i8 v[42:45], v[186:189], v[210:213], v[42:45]
	v_mfma_i32_16x16x64_i8 v[34:37], v[194:197], v[210:213], v[34:37]
	v_mfma_i32_16x16x64_i8 v[26:29], v[186:189], v[218:221], v[26:29]
	v_mfma_i32_16x16x64_i8 v[18:21], v[194:197], v[218:221], v[18:21]
	v_mfma_i32_16x16x64_i8 v[10:13], v[186:189], v[226:229], v[10:13]
	v_mfma_i32_16x16x64_i8 v[2:5], v[194:197], v[226:229], v[2:5]
	s_setprio 0
	s_barrier
	s_add_i32 s57, s57, 2
	s_add_u32 s28, s28, 0x100
	s_addc_u32 s29, s29, 0
	s_add_u32 s55, s55, 0x100
	s_addc_u32 s56, s56, 0
	s_cmp_gt_u32 s57, 13
	s_cbranch_scc0 .LBB0_2470
	s_and_b64 vcc, exec, s[12:13]
	s_cbranch_vccz .LBB0_2473
	s_barrier

.LBB0_3387:
	ds_read_b128 v[146:149], v177
	ds_read_b128 v[150:153], v177 offset:1024
	ds_read_b128 v[154:157], v177 offset:2048
	ds_read_b128 v[158:161], v177 offset:3072
	ds_read_b128 v[182:185], v178
	ds_read_b128 v[186:189], v178 offset:1024
	ds_read_b128 v[190:193], v178 offset:2048
	ds_read_b128 v[194:197], v178 offset:3072
	s_add_u32 s28, s26, 0xfffc0080
	s_addc_u32 s29, s27, -1
	s_cmp_eq_u32 s54, 12
	s_cselect_b32 s31, s19, s29
	s_cselect_b32 s30, s50, s28
	s_cselect_b32 s29, s17, s53
	s_cselect_b32 s28, s51, s52
	v_lshl_add_u64 v[162:163], s[26:27], 0, v[138:139]
	s_add_i32 m0, s25, 0xc000
	ds_read_b128 v[198:201], v179
	ds_read_b128 v[202:205], v179 offset:1024
	ds_read_b128 v[206:209], v179 offset:2048
	ds_read_b128 v[210:213], v179 offset:3072
	ds_read_b128 v[214:217], v179 offset:4096
	ds_read_b128 v[218:221], v179 offset:5120
	ds_read_b128 v[222:225], v179 offset:6144
	ds_read_b128 v[226:229], v179 offset:7168
	global_load_lds_dwordx4 v[162:163], off
	v_lshl_add_u64 v[162:163], s[26:27], 0, v[140:141]
	s_add_i32 m0, s25, 0xe000
	s_nop 0
	global_load_lds_dwordx4 v[162:163], off
	s_waitcnt vmcnt(8)
	s_waitcnt lgkmcnt(0)
	s_barrier
	s_setprio 1
	s_waitcnt lgkmcnt(0)
	v_mfma_i32_16x16x64_i8 v[126:129], v[146:149], v[198:201], v[126:129]
	v_mfma_i32_16x16x64_i8 v[118:121], v[154:157], v[198:201], v[118:121]
	v_mfma_i32_16x16x64_i8 v[110:113], v[146:149], v[206:209], v[110:113]
	v_mfma_i32_16x16x64_i8 v[102:105], v[154:157], v[206:209], v[102:105]
	v_mfma_i32_16x16x64_i8 v[94:97], v[146:149], v[214:217], v[94:97]
	v_mfma_i32_16x16x64_i8 v[86:89], v[154:157], v[214:217], v[86:89]
	v_mfma_i32_16x16x64_i8 v[78:81], v[146:149], v[222:225], v[78:81]
	v_mfma_i32_16x16x64_i8 v[70:73], v[154:157], v[222:225], v[70:73]
	v_mfma_i32_16x16x64_i8 v[126:129], v[150:153], v[202:205], v[126:129]
	v_mfma_i32_16x16x64_i8 v[118:121], v[158:161], v[202:205], v[118:121]
	v_mfma_i32_16x16x64_i8 v[110:113], v[150:153], v[210:213], v[110:113]
	v_mfma_i32_16x16x64_i8 v[102:105], v[158:161], v[210:213], v[102:105]
	v_mfma_i32_16x16x64_i8 v[94:97], v[150:153], v[218:221], v[94:97]
	v_mfma_i32_16x16x64_i8 v[86:89], v[158:161], v[218:221], v[86:89]
	v_mfma_i32_16x16x64_i8 v[78:81], v[150:153], v[226:229], v[78:81]
	v_mfma_i32_16x16x64_i8 v[70:73], v[158:161], v[226:229], v[70:73]
	s_setprio 0
	s_setprio 1
	v_mfma_i32_16x16x64_i8 v[122:125], v[182:185], v[198:201], v[122:125]
	v_mfma_i32_16x16x64_i8 v[114:117], v[190:193], v[198:201], v[114:117]
	v_mfma_i32_16x16x64_i8 v[106:109], v[182:185], v[206:209], v[106:109]
	v_mfma_i32_16x16x64_i8 v[98:101], v[190:193], v[206:209], v[98:101]
	v_mfma_i32_16x16x64_i8 v[90:93], v[182:185], v[214:217], v[90:93]
	v_mfma_i32_16x16x64_i8 v[82:85], v[190:193], v[214:217], v[82:85]
	v_mfma_i32_16x16x64_i8 v[74:77], v[182:185], v[222:225], v[74:77]
	v_mfma_i32_16x16x64_i8 v[66:69], v[190:193], v[222:225], v[66:69]
	v_mfma_i32_16x16x64_i8 v[122:125], v[186:189], v[202:205], v[122:125]
	v_mfma_i32_16x16x64_i8 v[114:117], v[194:197], v[202:205], v[114:117]
	v_mfma_i32_16x16x64_i8 v[106:109], v[186:189], v[210:213], v[106:109]
	v_mfma_i32_16x16x64_i8 v[98:101], v[194:197], v[210:213], v[98:101]
	v_mfma_i32_16x16x64_i8 v[90:93], v[186:189], v[218:221], v[90:93]
	v_mfma_i32_16x16x64_i8 v[82:85], v[194:197], v[218:221], v[82:85]
	v_mfma_i32_16x16x64_i8 v[74:77], v[186:189], v[226:229], v[74:77]
	v_mfma_i32_16x16x64_i8 v[66:69], v[194:197], v[226:229], v[66:69]
	s_setprio 0
	s_barrier
	s_add_i32 s55, s43, s35
	v_lshl_add_u64 v[162:163], s[28:29], 0, v[134:135]
	s_mov_b32 m0, s55
	ds_read_b128 v[198:201], v179 offset:16384
	ds_read_b128 v[202:205], v179 offset:17408
	ds_read_b128 v[206:209], v179 offset:18432
	ds_read_b128 v[210:213], v179 offset:19456
	ds_read_b128 v[214:217], v179 offset:20480
	ds_read_b128 v[218:221], v179 offset:21504
	ds_read_b128 v[222:225], v179 offset:22528
	ds_read_b128 v[226:229], v179 offset:23552
	global_load_lds_dwordx4 v[162:163], off nt
	s_add_i32 m0, s55, 0x2000
	s_add_u32 s56, s28, 0x40000
	v_lshl_add_u64 v[230:231], s[28:29], 0, v[130:131]
	s_addc_u32 s57, s29, 0
	s_add_i32 s55, s44, s35
	global_load_lds_dwordx4 v[230:231], off nt
	v_lshl_add_u64 v[232:233], s[56:57], 0, v[134:135]
	s_mov_b32 m0, s55
	v_lshl_add_u64 v[234:235], s[30:31], 0, v[132:133]
	global_load_lds_dwordx4 v[232:233], off nt
	v_lshl_add_u64 v[232:233], s[56:57], 0, v[130:131]
	s_add_i32 m0, s55, 0x2000
	s_nop 0
	global_load_lds_dwordx4 v[232:233], off nt
	v_lshl_add_u64 v[232:233], s[30:31], 0, v[136:137]
	s_mov_b32 m0, s25
	s_nop 0
	global_load_lds_dwordx4 v[232:233], off
	s_mov_b32 m0, s37
	s_nop 0
	global_load_lds_dwordx4 v[234:235], off
	s_waitcnt vmcnt(8)
	s_waitcnt lgkmcnt(0)
	s_barrier
	s_setprio 1
	s_waitcnt lgkmcnt(0)
	v_mfma_i32_16x16x64_i8 v[62:65], v[146:149], v[198:201], v[62:65]
	v_mfma_i32_16x16x64_i8 v[54:57], v[154:157], v[198:201], v[54:57]
	v_mfma_i32_16x16x64_i8 v[46:49], v[146:149], v[206:209], v[46:49]
	v_mfma_i32_16x16x64_i8 v[38:41], v[154:157], v[206:209], v[38:41]
	v_mfma_i32_16x16x64_i8 v[30:33], v[146:149], v[214:217], v[30:33]
	v_mfma_i32_16x16x64_i8 v[22:25], v[154:157], v[214:217], v[22:25]
	v_mfma_i32_16x16x64_i8 v[14:17], v[146:149], v[222:225], v[14:17]
	v_mfma_i32_16x16x64_i8 v[6:9], v[154:157], v[222:225], v[6:9]
	v_mfma_i32_16x16x64_i8 v[62:65], v[150:153], v[202:205], v[62:65]
	v_mfma_i32_16x16x64_i8 v[54:57], v[158:161], v[202:205], v[54:57]
	v_mfma_i32_16x16x64_i8 v[46:49], v[150:153], v[210:213], v[46:49]
	v_mfma_i32_16x16x64_i8 v[38:41], v[158:161], v[210:213], v[38:41]
	v_mfma_i32_16x16x64_i8 v[30:33], v[150:153], v[218:221], v[30:33]
	v_mfma_i32_16x16x64_i8 v[22:25], v[158:161], v[218:221], v[22:25]
	v_mfma_i32_16x16x64_i8 v[14:17], v[150:153], v[226:229], v[14:17]
	v_mfma_i32_16x16x64_i8 v[6:9], v[158:161], v[226:229], v[6:9]
	s_setprio 0
	s_setprio 1
	v_mfma_i32_16x16x64_i8 v[58:61], v[182:185], v[198:201], v[58:61]
	v_mfma_i32_16x16x64_i8 v[50:53], v[190:193], v[198:201], v[50:53]
	v_mfma_i32_16x16x64_i8 v[42:45], v[182:185], v[206:209], v[42:45]
	v_mfma_i32_16x16x64_i8 v[34:37], v[190:193], v[206:209], v[34:37]
	v_mfma_i32_16x16x64_i8 v[26:29], v[182:185], v[214:217], v[26:29]
	v_mfma_i32_16x16x64_i8 v[18:21], v[190:193], v[214:217], v[18:21]
	v_mfma_i32_16x16x64_i8 v[10:13], v[182:185], v[222:225], v[10:13]
	v_mfma_i32_16x16x64_i8 v[2:5], v[190:193], v[222:225], v[2:5]
	v_mfma_i32_16x16x64_i8 v[58:61], v[186:189], v[202:205], v[58:61]
	v_mfma_i32_16x16x64_i8 v[50:53], v[194:197], v[202:205], v[50:53]
	v_mfma_i32_16x16x64_i8 v[42:45], v[186:189], v[210:213], v[42:45]
	v_mfma_i32_16x16x64_i8 v[34:37], v[194:197], v[210:213], v[34:37]
	v_mfma_i32_16x16x64_i8 v[26:29], v[186:189], v[218:221], v[26:29]
	v_mfma_i32_16x16x64_i8 v[18:21], v[194:197], v[218:221], v[18:21]
	v_mfma_i32_16x16x64_i8 v[10:13], v[186:189], v[226:229], v[10:13]
	v_mfma_i32_16x16x64_i8 v[2:5], v[194:197], v[226:229], v[2:5]
	s_setprio 0
	s_barrier
	s_add_i32 s55, 0, 0x18000
	v_add_u32_e32 v158, s55, v168
	ds_read_b128 v[146:149], v158
	ds_read_b128 v[150:153], v158 offset:1024
	ds_read_b128 v[154:157], v158 offset:2048
	ds_read_b128 v[158:161], v158 offset:3072
	ds_read_b128 v[182:185], v180
	ds_read_b128 v[186:189], v180 offset:1024
	ds_read_b128 v[190:193], v180 offset:2048
	ds_read_b128 v[194:197], v180 offset:3072
	s_add_u32 s30, s30, 0x40000
	s_addc_u32 s31, s31, 0
	s_mov_b32 m0, s38
	v_lshl_add_u64 v[236:237], s[30:31], 0, v[136:137]
	ds_read_b128 v[198:201], v179 offset:32768
	ds_read_b128 v[202:205], v179 offset:33792
	ds_read_b128 v[206:209], v179 offset:34816
	ds_read_b128 v[210:213], v179 offset:35840
	ds_read_b128 v[214:217], v179 offset:36864
	ds_read_b128 v[218:221], v179 offset:37888
	ds_read_b128 v[222:225], v179 offset:38912
	ds_read_b128 v[226:229], v179 offset:39936
	global_load_lds_dwordx4 v[236:237], off
	v_lshl_add_u64 v[236:237], s[30:31], 0, v[132:133]
	s_mov_b32 m0, s39
	s_nop 0
	global_load_lds_dwordx4 v[236:237], off
	s_waitcnt vmcnt(8)
	s_waitcnt lgkmcnt(0)
	s_barrier
	s_setprio 1
	s_waitcnt lgkmcnt(0)
	v_mfma_i32_16x16x64_i8 v[126:129], v[146:149], v[198:201], v[126:129]
	v_mfma_i32_16x16x64_i8 v[118:121], v[154:157], v[198:201], v[118:121]
	v_mfma_i32_16x16x64_i8 v[110:113], v[146:149], v[206:209], v[110:113]
	v_mfma_i32_16x16x64_i8 v[102:105], v[154:157], v[206:209], v[102:105]
	v_mfma_i32_16x16x64_i8 v[94:97], v[146:149], v[214:217], v[94:97]
	v_mfma_i32_16x16x64_i8 v[86:89], v[154:157], v[214:217], v[86:89]
	v_mfma_i32_16x16x64_i8 v[78:81], v[146:149], v[222:225], v[78:81]
	v_mfma_i32_16x16x64_i8 v[70:73], v[154:157], v[222:225], v[70:73]
	v_mfma_i32_16x16x64_i8 v[126:129], v[150:153], v[202:205], v[126:129]
	v_mfma_i32_16x16x64_i8 v[118:121], v[158:161], v[202:205], v[118:121]
	v_mfma_i32_16x16x64_i8 v[110:113], v[150:153], v[210:213], v[110:113]
	v_mfma_i32_16x16x64_i8 v[102:105], v[158:161], v[210:213], v[102:105]
	v_mfma_i32_16x16x64_i8 v[94:97], v[150:153], v[218:221], v[94:97]
	v_mfma_i32_16x16x64_i8 v[86:89], v[158:161], v[218:221], v[86:89]
	v_mfma_i32_16x16x64_i8 v[78:81], v[150:153], v[226:229], v[78:81]
	v_mfma_i32_16x16x64_i8 v[70:73], v[158:161], v[226:229], v[70:73]
	s_setprio 0
	s_setprio 1
	v_mfma_i32_16x16x64_i8 v[122:125], v[182:185], v[198:201], v[122:125]
	v_mfma_i32_16x16x64_i8 v[114:117], v[190:193], v[198:201], v[114:117]
	v_mfma_i32_16x16x64_i8 v[106:109], v[182:185], v[206:209], v[106:109]
	v_mfma_i32_16x16x64_i8 v[98:101], v[190:193], v[206:209], v[98:101]
	v_mfma_i32_16x16x64_i8 v[90:93], v[182:185], v[214:217], v[90:93]
	v_mfma_i32_16x16x64_i8 v[82:85], v[190:193], v[214:217], v[82:85]
	v_mfma_i32_16x16x64_i8 v[74:77], v[182:185], v[222:225], v[74:77]
	v_mfma_i32_16x16x64_i8 v[66:69], v[190:193], v[222:225], v[66:69]
	v_mfma_i32_16x16x64_i8 v[122:125], v[186:189], v[202:205], v[122:125]
	v_mfma_i32_16x16x64_i8 v[114:117], v[194:197], v[202:205], v[114:117]
	v_mfma_i32_16x16x64_i8 v[106:109], v[186:189], v[210:213], v[106:109]
	v_mfma_i32_16x16x64_i8 v[98:101], v[194:197], v[210:213], v[98:101]
	v_mfma_i32_16x16x64_i8 v[90:93], v[186:189], v[218:221], v[90:93]
	v_mfma_i32_16x16x64_i8 v[82:85], v[194:197], v[218:221], v[82:85]
	v_mfma_i32_16x16x64_i8 v[74:77], v[186:189], v[226:229], v[74:77]
	v_mfma_i32_16x16x64_i8 v[66:69], v[194:197], v[226:229], v[66:69]
	s_setprio 0
	s_barrier
	s_add_i32 s30, s55, s35
	v_lshl_add_u64 v[162:163], v[162:163], 0, s[8:9]
	s_mov_b32 m0, s30
	ds_read_b128 v[198:201], v179 offset:49152
	ds_read_b128 v[202:205], v179 offset:50176
	ds_read_b128 v[206:209], v179 offset:51200
	ds_read_b128 v[210:213], v179 offset:52224
	ds_read_b128 v[214:217], v179 offset:53248
	ds_read_b128 v[218:221], v179 offset:54272
	ds_read_b128 v[222:225], v179 offset:55296
	ds_read_b128 v[226:229], v179 offset:56320
	global_load_lds_dwordx4 v[162:163], off nt
	s_add_i32 m0, s30, 0x2000
	s_add_u32 s28, s28, 0x40080
	v_lshl_add_u64 v[162:163], v[230:231], 0, s[8:9]
	s_addc_u32 s29, s29, 0
	s_add_i32 s30, s45, s35
	global_load_lds_dwordx4 v[162:163], off nt
	v_lshl_add_u64 v[162:163], s[28:29], 0, v[134:135]
	s_mov_b32 m0, s30
	s_nop 0
	global_load_lds_dwordx4 v[162:163], off nt
	v_lshl_add_u64 v[162:163], s[28:29], 0, v[130:131]
	s_add_i32 m0, s30, 0x2000
	s_nop 0
	global_load_lds_dwordx4 v[162:163], off nt
	v_lshl_add_u64 v[162:163], v[232:233], 0, s[8:9]
	s_mov_b32 m0, s40
	s_nop 0
	global_load_lds_dwordx4 v[162:163], off
	v_lshl_add_u64 v[162:163], v[234:235], 0, s[8:9]
	s_mov_b32 m0, s41
	s_nop 0
	global_load_lds_dwordx4 v[162:163], off
	s_waitcnt vmcnt(8)
	s_waitcnt lgkmcnt(0)
	s_barrier
	s_setprio 1
	s_waitcnt lgkmcnt(0)
	v_mfma_i32_16x16x64_i8 v[62:65], v[146:149], v[198:201], v[62:65]
	v_mfma_i32_16x16x64_i8 v[54:57], v[154:157], v[198:201], v[54:57]
	v_mfma_i32_16x16x64_i8 v[46:49], v[146:149], v[206:209], v[46:49]
	v_mfma_i32_16x16x64_i8 v[38:41], v[154:157], v[206:209], v[38:41]
	v_mfma_i32_16x16x64_i8 v[30:33], v[146:149], v[214:217], v[30:33]
	v_mfma_i32_16x16x64_i8 v[22:25], v[154:157], v[214:217], v[22:25]
	v_mfma_i32_16x16x64_i8 v[14:17], v[146:149], v[222:225], v[14:17]
	v_mfma_i32_16x16x64_i8 v[6:9], v[154:157], v[222:225], v[6:9]
	v_mfma_i32_16x16x64_i8 v[62:65], v[150:153], v[202:205], v[62:65]
	v_mfma_i32_16x16x64_i8 v[54:57], v[158:161], v[202:205], v[54:57]
	v_mfma_i32_16x16x64_i8 v[46:49], v[150:153], v[210:213], v[46:49]
	v_mfma_i32_16x16x64_i8 v[38:41], v[158:161], v[210:213], v[38:41]
	v_mfma_i32_16x16x64_i8 v[30:33], v[150:153], v[218:221], v[30:33]
	v_mfma_i32_16x16x64_i8 v[22:25], v[158:161], v[218:221], v[22:25]
	v_mfma_i32_16x16x64_i8 v[14:17], v[150:153], v[226:229], v[14:17]
	v_mfma_i32_16x16x64_i8 v[6:9], v[158:161], v[226:229], v[6:9]
	s_setprio 0
	s_setprio 1
	v_mfma_i32_16x16x64_i8 v[58:61], v[182:185], v[198:201], v[58:61]
	v_mfma_i32_16x16x64_i8 v[50:53], v[190:193], v[198:201], v[50:53]
	v_mfma_i32_16x16x64_i8 v[42:45], v[182:185], v[206:209], v[42:45]
	v_mfma_i32_16x16x64_i8 v[34:37], v[190:193], v[206:209], v[34:37]
	v_mfma_i32_16x16x64_i8 v[26:29], v[182:185], v[214:217], v[26:29]
	v_mfma_i32_16x16x64_i8 v[18:21], v[190:193], v[214:217], v[18:21]
	v_mfma_i32_16x16x64_i8 v[10:13], v[182:185], v[222:225], v[10:13]
	v_mfma_i32_16x16x64_i8 v[2:5], v[190:193], v[222:225], v[2:5]
	v_mfma_i32_16x16x64_i8 v[58:61], v[186:189], v[202:205], v[58:61]
	v_mfma_i32_16x16x64_i8 v[50:53], v[194:197], v[202:205], v[50:53]
	v_mfma_i32_16x16x64_i8 v[42:45], v[186:189], v[210:213], v[42:45]
	v_mfma_i32_16x16x64_i8 v[34:37], v[194:197], v[210:213], v[34:37]
	v_mfma_i32_16x16x64_i8 v[26:29], v[186:189], v[218:221], v[26:29]
	v_mfma_i32_16x16x64_i8 v[18:21], v[194:197], v[218:221], v[18:21]
	v_mfma_i32_16x16x64_i8 v[10:13], v[186:189], v[226:229], v[10:13]
	v_mfma_i32_16x16x64_i8 v[2:5], v[194:197], v[226:229], v[2:5]
	s_setprio 0
	s_barrier
	s_add_i32 s54, s54, 2
	s_add_u32 s26, s26, 0x100
	s_addc_u32 s27, s27, 0
	s_add_u32 s52, s52, 0x100
	s_addc_u32 s53, s53, 0
	s_cmp_gt_u32 s54, 13
	s_cbranch_scc0 .LBB0_3387
	s_and_b64 vcc, exec, s[12:13]
	s_cbranch_vccz .LBB0_3390
	s_barrier
